# icache warm-up walker: idle waves hop through execz pads of next GEMM phase prologue/epilogue during grid barrier (on top of ctx remap)
# speedup vs baseline: 1.0039x; 1.0039x over previous
.Lpad_G2_0:
	s_cbranch_execz .Lpad_G2_7
	v_mul_i32_i24_e32 v4, 0x400, v10
	v_sub_u32_e32 v3, v3, v4
	v_lshrrev_b32_e32 v4, 4, v3
	s_add_u32 s12, s60, 0xba00000
	v_bitop3_b32 v3, v4, v3, 32 bitop3:0x6c
	s_addc_u32 s13, s61, 0
	s_ashr_i32 s5, s4, 31
.Lpad_G2_1:
	s_cbranch_execz .Lpad_G2_8
	v_ashrrev_i32_e32 v4, 31, v3
	s_lshl_b64 s[6:7], s[4:5], 25
	v_lshrrev_b32_e32 v4, 26, v4
	s_add_u32 s5, s60, s6
	v_add_u32_e32 v4, v3, v4
	v_lshlrev_b32_e32 v5, 3, v10
	s_addc_u32 s6, s61, s7
.Lpad_G2_2:
	s_cbranch_execz .Lpad_G2_9
	v_ashrrev_i32_e32 v11, 6, v4
	v_and_b32_e32 v5, -16, v5
	s_add_u32 s5, s5, 0x3800000
	v_add_u32_e32 v5, v11, v5
	s_addc_u32 s14, s6, 0
	v_and_b32_e32 v6, 3, v11
	s_mov_b32 s6, 0xfffe0
.Lpad_G2_3:
	s_cbranch_execz .Lpad_G2_10
	v_lshrrev_b32_e32 v7, 2, v5
	v_lshlrev_b32_e32 v8, 1, v5
	v_and_b32_e32 v4, 0xc0, v4
	v_and_or_b32 v6, v5, s6, v6
	v_and_b32_e32 v7, 4, v7
	v_and_b32_e32 v8, 24, v8
	v_sub_u32_e32 v3, v3, v4
.Lpad_G2_4:
	s_cbranch_execz .Lpad_G2_11
	v_or3_b32 v6, v6, v7, v8
	v_lshlrev_b32_e32 v7, 5, v10
	v_ashrrev_i16_sdwa v3, v225, sext(v3) dst_sel:DWORD dst_unused:UNUSED_PAD src0_sel:DWORD src1_sel:BYTE_0
	v_and_b32_e32 v7, 32, v7
	v_bfe_i32 v12, v3, 0, 16
	v_add_lshl_u32 v3, v7, v12, 1
	v_lshl_add_u32 v130, v6, 12, v3
.Lpad_G2_5:
	s_cbranch_execz .Lpad_G2_12
	v_lshl_add_u32 v132, v5, 12, v3
	v_bfe_i32 v3, v0, 27, 1
	v_lshrrev_b32_e32 v3, 22, v3
	v_add_u32_e32 v3, v2, v3
	v_and_b32_e32 v3, 0xfffffc00, v3
	v_sub_u32_e32 v2, v2, v3
	v_lshrrev_b32_e32 v3, 4, v2
.Lpad_G2_6:
	s_cbranch_execz .Lpad_G2_13
	v_ashrrev_i32_e32 v4, 31, v0
	v_bitop3_b32 v2, v3, v2, 32 bitop3:0x6c
	v_lshrrev_b32_e32 v4, 26, v4
	v_ashrrev_i32_e32 v3, 31, v2
	v_add_u32_e32 v4, v0, v4
	v_lshrrev_b32_e32 v3, 26, v3
	v_ashrrev_i32_e32 v14, 6, v4
.Lpad_G2_7:
	s_cbranch_execz .Lpad_G2_14
	v_add_u32_e32 v3, v2, v3
	v_lshlrev_b32_e32 v4, 3, v14
	v_ashrrev_i32_e32 v13, 6, v3
	v_and_b32_e32 v4, -16, v4
	v_add_u32_e32 v4, v13, v4
	v_and_b32_e32 v5, 3, v13
	v_lshrrev_b32_e32 v6, 2, v4
.Lpad_G2_8:
	s_cbranch_execz .Lpad_G2_15
	v_lshlrev_b32_e32 v7, 1, v4
	v_and_b32_e32 v3, 0xc0, v3
	s_ashr_i32 s38, s10, 6
	v_and_or_b32 v5, v4, s6, v5
	v_and_b32_e32 v6, 4, v6
	v_and_b32_e32 v7, 24, v7
	v_sub_u32_e32 v2, v2, v3
.Lpad_G2_9:
	s_cbranch_execz .Lpad_G2_16
	s_ashr_i32 s11, s10, 8
	s_lshl_b32 s15, s38, 10
	v_or3_b32 v5, v5, v6, v7
	v_lshlrev_b32_e32 v6, 5, v14
	v_ashrrev_i16_sdwa v2, v225, sext(v2) dst_sel:DWORD dst_unused:UNUSED_PAD src0_sel:DWORD src1_sel:BYTE_0
	v_readlane_b32 s6, v254, 29
	v_and_b32_e32 v6, 32, v6
.Lpad_G2_10:
	s_cbranch_execz .Lpad_G2_17
	v_bfe_i32 v15, v2, 0, 16
	v_readlane_b32 s7, v254, 30
	s_add_u32 s8, s5, s6
	v_add_lshl_u32 v2, v6, v15, 1
	s_addc_u32 s9, s14, s7
	s_add_i32 s16, s15, 0
	v_lshl_add_u32 v134, v5, 12, v2
.Lpad_G2_11:
	s_cbranch_execz .Lpad_G2_18
	s_add_i32 m0, s16, 0x10000
	v_lshl_add_u32 v136, v4, 12, v2
	global_load_lds_dwordx4 v134, s[8:9]
	s_add_i32 m0, s16, 0x12000
	s_add_u32 s6, s8, 0x80000
	global_load_lds_dwordx4 v130, s[8:9]
	s_addc_u32 s7, s9, 0
.Lpad_G2_12:
	s_cbranch_execz .Lpad_G2_19
	s_add_i32 m0, s16, 0x14000
	v_mov_b32_e32 v135, v1
	global_load_lds_dwordx4 v134, s[6:7]
	s_add_i32 m0, s16, 0x16000
	v_mov_b32_e32 v131, v1
	global_load_lds_dwordx4 v130, s[6:7]
	v_readlane_b32 s6, v254, 38
.Lpad_G2_13:
	s_cbranch_execz .Lpad_G2_20
	v_readlane_b32 s7, v254, 39
	s_add_u32 s6, s12, s6
	s_addc_u32 s7, s13, s7
	s_add_i32 s17, s16, 0x2000
	s_mov_b32 m0, s16
	s_add_u32 s20, s6, 0x80000
	global_load_lds_dwordx4 v136, s[6:7]
.Lpad_G2_14:
	s_cbranch_execz .Lpad_G2_21
	s_mov_b32 m0, s17
	s_addc_u32 s21, s7, 0
	s_add_i32 s18, s16, 0x4000
	global_load_lds_dwordx4 v132, s[6:7]
	s_mov_b32 m0, s18
	s_add_i32 s19, s16, 0x6000
	global_load_lds_dwordx4 v136, s[20:21]
.Lpad_G2_15:
	s_cbranch_execz .Lpad_G2_22
	s_mov_b32 m0, s19
	v_mov_b32_e32 v137, v1
	global_load_lds_dwordx4 v132, s[20:21]
	v_mov_b32_e32 v133, v1
	s_cmp_eq_u32 s11, 1
	v_lshl_add_u64 v[8:9], s[8:9], 0, v[134:135]
	v_lshl_add_u64 v[6:7], s[8:9], 0, v[130:131]
.Lpad_G2_16:
	s_cbranch_execz .Lpad_G2_23
	v_lshl_add_u64 v[2:3], s[6:7], 0, v[136:137]
	s_cselect_b64 s[28:29], -1, 0
	s_cmp_lg_u32 s11, 1
	v_lshl_add_u64 v[4:5], s[6:7], 0, v[132:133]
	s_cbranch_scc1 .LBB0_26
	s_barrier

.Lpad_G2_17:
	s_cbranch_execz .Lpad_G2_24
	v_lshlrev_b32_e32 v17, 6, v0
	s_movk_i32 s40, 0x3c0
	s_add_u32 s20, s60, 0x17a00000
	v_and_or_b32 v16, v17, s40, v16
	v_lshlrev_b32_e32 v17, 2, v0
	s_addc_u32 s21, s61, 0
	s_and_b32 s44, s38, 3
.Lpad_G2_18:
	s_cbranch_execz .Lpad_G2_25
	s_lshl_b32 s38, s11, 6
	s_lshl_b32 s11, s11, 13
	v_and_b32_e32 v17, 32, v17
	s_add_i32 m0, s16, 0x18000
	v_lshl_add_u64 v[8:9], v[8:9], 0, s[34:35]
	v_bitop3_b32 v18, v16, s11, v17 bitop3:0xde
	s_lshl_b32 s11, s44, 12
.Lpad_G2_19:
	s_cbranch_execz .Lpad_G2_26
	s_waitcnt vmcnt(2)
	s_barrier
	global_load_lds_dwordx4 v[8:9], off
	v_lshl_add_u64 v[6:7], v[6:7], 0, s[34:35]
	s_add_i32 m0, s16, 0x1a000
	s_add_i32 s49, s16, 0x8000
	s_add_i32 s56, s16, 0xa000
.Lpad_G2_20:
	s_cbranch_execz .Lpad_G2_27
	global_load_lds_dwordx4 v[6:7], off
	v_lshl_add_u64 v[2:3], v[2:3], 0, s[34:35]
	s_mov_b32 m0, s49
	s_add_u32 s40, s8, 0x80080
	global_load_lds_dwordx4 v[2:3], off
	v_lshl_add_u64 v[2:3], v[4:5], 0, s[34:35]
	s_mov_b32 m0, s56
.Lpad_G2_21:
	s_cbranch_execz .Lpad_G2_28
	s_addc_u32 s41, s9, 0
	global_load_lds_dwordx4 v[2:3], off
	s_add_i32 m0, s16, 0x1c000
	v_lshl_add_u64 v[2:3], s[40:41], 0, v[134:135]
	global_load_lds_dwordx4 v[2:3], off
	v_lshl_add_u64 v[2:3], s[40:41], 0, v[130:131]
	s_add_i32 m0, s16, 0x1e000
.Lpad_G2_22:
	s_cbranch_execz .Lpad_G2_29
	v_and_b32_e32 v145, 63, v0
	global_load_lds_dwordx4 v[2:3], off
	v_lshlrev_b32_e32 v0, 15, v14
	v_and_b32_e32 v0, 0xffff0000, v0
	v_lshl_add_u32 v0, v13, 12, v0
	v_and_b32_e32 v2, 1, v14
	v_lshl_or_b32 v0, v2, 6, v0
.Lpad_G2_23:
	s_cbranch_execz .Lpad_G2_30
	v_lshl_add_u32 v138, v15, 1, v0
	v_lshlrev_b32_e32 v0, 15, v10
	v_and_b32_e32 v0, 0xffff0000, v0
	s_waitcnt vmcnt(6)
	v_lshl_add_u32 v0, v11, 12, v0
	v_and_b32_e32 v2, 1, v10
	v_bitop3_b32 v144, v16, s11, v17 bitop3:0xde
.Lpad_G2_24:
	s_cbranch_execz .Lpad_G2_31
	s_cmpk_lt_u32 s10, 0x100
	v_lshl_or_b32 v0, v2, 6, v0
	v_readlane_b32 s10, v254, 36
	s_cselect_b64 s[42:43], -1, 0
	s_lshl_b32 s57, s44, 6
	v_mov_b32_e32 v139, v1
	v_lshl_add_u32 v140, v12, 1, v0
.Lpad_G2_25:
	s_cbranch_execz .Lpad_G2_32
	v_mov_b32_e32 v141, v1
	s_mov_b32 s58, 0
	v_add_u32_e32 v146, 0, v18
	v_readlane_b32 s59, v254, 28
	s_mov_b32 s62, s10
	s_barrier
	v_readlane_b32 s11, v254, 37
.Lpad_G2_26:
	s_cbranch_execz .Lpad_G2_33
	s_branch .LBB0_29

.Lpad_G2_27:
	s_cbranch_execz .Lpad_G2_34
	s_cbranch_vccz .LBB0_42

.Lpad_G2_28:
	s_cbranch_execz .Lpad_G2_35
	s_addc_u32 s11, s11, s76
	v_mov_b64_e32 v[2:3], 0x800
	v_cmp_lt_i64_e64 s[40:41], s[10:11], v[2:3]
	v_mov_b64_e32 v[2:3], 0x7ff
	v_cmp_gt_i64_e32 vcc, s[10:11], v[2:3]
	s_cbranch_vccnz .LBB0_35
	s_ashr_i32 s11, s10, 31
.Lpad_G2_29:
	s_cbranch_execz .Lpad_G2_36
	s_lshr_b32 s11, s11, 29
	s_add_i32 s44, s10, s11
	s_and_b32 s11, s44, -8
	s_sub_i32 s45, s10, s11
	s_cmp_gt_i32 s45, -1
	s_mov_b64 s[10:11], -1
	s_cbranch_scc0 .LBB0_32
.Lpad_G2_30:
	s_cbranch_execz .Lpad_G2_37
	s_lshl_b32 s46, s45, 8
	s_mov_b64 s[10:11], 0

.Lpad_G2_31:
	s_cbranch_execz .Lpad_G2_38
	s_ashr_i32 s11, s10, 31
	s_lshr_b32 s11, s11, 25
	s_add_i32 s11, s10, s11
	s_ashr_i32 s44, s11, 7
	s_lshl_b32 s45, s44, 2
	s_sub_i32 s44, 64, s45
	s_min_i32 s46, s44, 4
.Lpad_G2_32:
	s_cbranch_execz .Lpad_G2_39
	s_abs_i32 s44, s46
	v_cvt_f32_u32_e32 v0, s44
	s_sub_i32 s52, 0, s44
	s_and_b32 s11, s11, 0xffffff80
	s_sub_i32 s10, s10, s11
	v_rcp_iflag_f32_e32 v0, v0
	s_abs_i32 s11, s10
.Lpad_G2_33:
	s_cbranch_execz .Lpad_G2_40
	s_xor_b32 s47, s10, s46
	s_ashr_i32 s47, s47, 31
	v_mul_f32_e32 v0, 0x4f7ffffe, v0
	v_cvt_u32_f32_e32 v0, v0
	s_nop 0
	v_readfirstlane_b32 s53, v0
	s_mul_i32 s52, s52, s53
.Lpad_G2_34:
	s_cbranch_execz .Lpad_G2_41
	s_mul_hi_u32 s52, s53, s52
	s_add_i32 s53, s53, s52
	s_mul_hi_u32 s52, s11, s53
	s_mul_i32 s53, s52, s44
	s_sub_i32 s11, s11, s53
	s_add_i32 s54, s52, 1
	s_sub_i32 s53, s11, s44
.Lpad_G2_35:
	s_cbranch_execz .Lpad_G2_42
	s_cmp_ge_u32 s11, s44
	s_cselect_b32 s52, s54, s52
	s_cselect_b32 s11, s53, s11
	s_add_i32 s53, s52, 1
	s_cmp_ge_u32 s11, s44
	s_cselect_b32 s11, s53, s52
	s_xor_b32 s11, s11, s47
.Lpad_G2_36:
	s_cbranch_execz .Lpad_G2_43
	s_sub_i32 s44, s11, s47
	s_mul_i32 s11, s44, s46
	s_sub_i32 s10, s10, s11
	s_add_i32 s46, s45, s10

.Lpad_G2_37:
	s_cbranch_execz .Lpad_G2_44
	s_addc_u32 s53, s13, s11
	s_and_b64 s[10:11], s[40:41], exec
	s_cselect_b32 s47, s53, s7
	s_cselect_b32 s63, s52, s6
	s_ashr_i32 s45, s44, 31
	s_lshl_b64 s[10:11], s[44:45], 20
	s_add_u32 s54, s5, s10
.Lpad_G2_38:
	s_cbranch_execz .Lpad_G2_45
	s_addc_u32 s55, s14, s11
	s_and_b64 s[10:11], s[40:41], exec
	s_cselect_b32 s45, s55, s9
	s_cselect_b32 s64, s54, s8
	s_add_u32 s6, s6, 0x80080
	s_addc_u32 s7, s7, 0
	s_add_u32 s65, s8, 0x100
.Lpad_G2_39:
	s_cbranch_execz .Lpad_G2_46
	v_mov_b32_e32 v2, 0
	s_addc_u32 s66, s9, 0
	s_mov_b32 s67, -2
	v_mov_b32_e32 v3, v2
	v_mov_b32_e32 v4, v2
	v_mov_b32_e32 v5, v2
	v_mov_b32_e32 v6, v2
.Lpad_G2_40:
	s_cbranch_execz .Lpad_G2_47
	v_mov_b32_e32 v7, v2
	v_mov_b32_e32 v8, v2
	v_mov_b32_e32 v9, v2
	v_mov_b32_e32 v18, v2
	v_mov_b32_e32 v19, v2
	v_mov_b32_e32 v20, v2
	v_mov_b32_e32 v21, v2
.Lpad_G2_41:
	s_cbranch_execz .Lpad_G2_48
	v_mov_b32_e32 v22, v2
	v_mov_b32_e32 v23, v2
	v_mov_b32_e32 v24, v2
	v_mov_b32_e32 v25, v2
	v_mov_b32_e32 v34, v2
	v_mov_b32_e32 v35, v2
	v_mov_b32_e32 v36, v2
.Lpad_G2_42:
	s_cbranch_execz .Lpad_G2_49
	v_mov_b32_e32 v37, v2
	v_mov_b32_e32 v38, v2
	v_mov_b32_e32 v39, v2
	v_mov_b32_e32 v40, v2
	v_mov_b32_e32 v41, v2
	v_mov_b32_e32 v50, v2
	v_mov_b32_e32 v51, v2
.Lpad_G2_43:
	s_cbranch_execz .Lpad_G2_50
	v_mov_b32_e32 v52, v2
	v_mov_b32_e32 v53, v2
	v_mov_b32_e32 v54, v2
	v_mov_b32_e32 v55, v2
	v_mov_b32_e32 v56, v2
	v_mov_b32_e32 v57, v2
	v_mov_b32_e32 v10, v2
.Lpad_G2_44:
	s_cbranch_execz .Lpad_G2_51
	v_mov_b32_e32 v11, v2
	v_mov_b32_e32 v12, v2
	v_mov_b32_e32 v13, v2
	v_mov_b32_e32 v14, v2
	v_mov_b32_e32 v15, v2
	v_mov_b32_e32 v16, v2
	v_mov_b32_e32 v17, v2
.Lpad_G2_45:
	s_cbranch_execz .Lpad_G2_52
	v_mov_b32_e32 v26, v2
	v_mov_b32_e32 v27, v2
	v_mov_b32_e32 v28, v2
	v_mov_b32_e32 v29, v2
	v_mov_b32_e32 v30, v2
	v_mov_b32_e32 v31, v2
	v_mov_b32_e32 v32, v2
.Lpad_G2_46:
	s_cbranch_execz .Lpad_G2_53
	v_mov_b32_e32 v33, v2
	v_mov_b32_e32 v42, v2
	v_mov_b32_e32 v43, v2
	v_mov_b32_e32 v44, v2
	v_mov_b32_e32 v45, v2
	v_mov_b32_e32 v46, v2
	v_mov_b32_e32 v47, v2
.Lpad_G2_47:
	s_cbranch_execz .Lpad_G2_54
	v_mov_b32_e32 v48, v2
	v_mov_b32_e32 v49, v2
	v_mov_b32_e32 v58, v2
	v_mov_b32_e32 v59, v2
	v_mov_b32_e32 v60, v2
	v_mov_b32_e32 v61, v2
	v_mov_b32_e32 v62, v2
.Lpad_G2_48:
	s_cbranch_execz .Lpad_G2_55
	v_mov_b32_e32 v63, v2
	v_mov_b32_e32 v64, v2
	v_mov_b32_e32 v65, v2
	v_mov_b32_e32 v66, v2
	v_mov_b32_e32 v67, v2
	v_mov_b32_e32 v68, v2
	v_mov_b32_e32 v69, v2
.Lpad_G2_49:
	s_cbranch_execz .Lpad_G2_56
	v_mov_b32_e32 v70, v2
	v_mov_b32_e32 v71, v2
	v_mov_b32_e32 v72, v2
	v_mov_b32_e32 v73, v2
	v_mov_b32_e32 v82, v2
	v_mov_b32_e32 v83, v2
	v_mov_b32_e32 v84, v2
.Lpad_G2_50:
	s_cbranch_execz .Lpad_G2_57
	v_mov_b32_e32 v85, v2
	v_mov_b32_e32 v86, v2
	v_mov_b32_e32 v87, v2
	v_mov_b32_e32 v88, v2
	v_mov_b32_e32 v89, v2
	v_mov_b32_e32 v98, v2
	v_mov_b32_e32 v99, v2
.Lpad_G2_51:
	s_cbranch_execz .Lpad_G2_58
	v_mov_b32_e32 v100, v2
	v_mov_b32_e32 v101, v2
	v_mov_b32_e32 v102, v2
	v_mov_b32_e32 v103, v2
	v_mov_b32_e32 v104, v2
	v_mov_b32_e32 v105, v2
	v_mov_b32_e32 v114, v2
.Lpad_G2_52:
	s_cbranch_execz .Lpad_G2_59
	v_mov_b32_e32 v115, v2
	v_mov_b32_e32 v116, v2
	v_mov_b32_e32 v117, v2
	v_mov_b32_e32 v118, v2
	v_mov_b32_e32 v119, v2
	v_mov_b32_e32 v120, v2
	v_mov_b32_e32 v121, v2
.Lpad_G2_53:
	s_cbranch_execz .Lpad_G2_60
	v_mov_b32_e32 v74, v2
	v_mov_b32_e32 v75, v2
	v_mov_b32_e32 v76, v2
	v_mov_b32_e32 v77, v2
	v_mov_b32_e32 v78, v2
	v_mov_b32_e32 v79, v2
	v_mov_b32_e32 v80, v2
.Lpad_G2_54:
	s_cbranch_execz .Lpad_G2_61
	v_mov_b32_e32 v81, v2
	v_mov_b32_e32 v90, v2
	v_mov_b32_e32 v91, v2
	v_mov_b32_e32 v92, v2
	v_mov_b32_e32 v93, v2
	v_mov_b32_e32 v94, v2
	v_mov_b32_e32 v95, v2
.Lpad_G2_55:
	s_cbranch_execz .Lpad_G2_62
	v_mov_b32_e32 v96, v2
	v_mov_b32_e32 v97, v2
	v_mov_b32_e32 v106, v2
	v_mov_b32_e32 v107, v2
	v_mov_b32_e32 v108, v2
	v_mov_b32_e32 v109, v2
	v_mov_b32_e32 v110, v2
.Lpad_G2_56:
	s_cbranch_execz .Lpad_G2_63
	v_mov_b32_e32 v111, v2
	v_mov_b32_e32 v112, v2
	v_mov_b32_e32 v113, v2
	v_mov_b32_e32 v122, v2
	v_mov_b32_e32 v123, v2
	v_mov_b32_e32 v124, v2
	v_mov_b32_e32 v125, v2
.Lpad_G2_57:
	s_cbranch_execz .Lpad_G2_64
	v_mov_b32_e32 v126, v2
	v_mov_b32_e32 v127, v2
	v_mov_b32_e32 v128, v2
	v_mov_b32_e32 v129, v2

.Lpad_G2_58:
	s_cbranch_execz .Lpad_G2_65
	s_lshl_b64 s[6:7], s[6:7], 14
	s_add_u32 s8, s20, s6
	v_max_f32_e32 v122, v122, v122
	s_addc_u32 s9, s21, s7
	s_lshl_b32 s6, s59, 8
	v_max_f32_e32 v122, 0, v122
	v_max_f32_e32 v123, v123, v123
.Lpad_G2_59:
	s_cbranch_execz .Lpad_G2_66
	v_max_f32_e32 v124, v124, v124
	v_mov_b32_e32 v0, v145
	s_ashr_i32 s7, s6, 31
	v_mul_f32_e32 v147, v122, v122
	v_max_f32_e32 v122, v127, v127
	v_max_f32_e32 v123, 0, v123
	v_max_f32_e32 v124, 0, v124
.Lpad_G2_60:
	s_cbranch_execz .Lpad_G2_67
	s_lshl_b64 s[6:7], s[6:7], 1
	v_and_or_b32 v142, v0, 15, s38
	v_max_f32_e32 v126, v126, v126
	v_max_f32_e32 v122, 0, v122
	v_mul_f32_e32 v127, v123, v123
	v_max_f32_e32 v123, v128, v128
	v_mul_f32_e32 v128, v124, v124
.Lpad_G2_61:
	s_cbranch_execz .Lpad_G2_68
	v_max_f32_e32 v124, v129, v129
	v_max_f32_e32 v125, v125, v125
	s_add_u32 s6, s8, s6
	v_lshlrev_b32_e32 v142, 14, v142
	v_and_b32_e32 v0, -16, v0
	v_max_f32_e32 v126, 0, v126
	v_mul_f32_e32 v122, v122, v122
.Lpad_G2_62:
	s_cbranch_execz .Lpad_G2_69
	v_max_f32_e32 v123, 0, v123
	v_max_f32_e32 v124, 0, v124
	v_max_f32_e32 v125, 0, v125
	v_max_f32_e32 v114, v114, v114
	v_max_f32_e32 v115, v115, v115
	v_max_f32_e32 v116, v116, v116
	s_addc_u32 s7, s9, s7
.Lpad_G2_63:
	s_cbranch_execz .Lpad_G2_70
	v_add3_u32 v0, v0, s57, v142
	v_mul_f32_e32 v126, v126, v126
	v_mul_f32_e32 v123, v123, v123
	v_mul_f32_e32 v124, v124, v124
	v_mul_f32_e32 v125, v125, v125
	v_cvt_pk_bf16_f32 v122, v126, v122
	v_max_f32_e32 v114, 0, v114
.Lpad_G2_64:
	s_cbranch_execz .Lpad_G2_71
	v_max_f32_e32 v115, 0, v115
	v_max_f32_e32 v116, 0, v116
	v_cvt_pk_bf16_f32 v123, v123, v124
	v_cvt_pk_bf16_f32 v124, v147, v127
	v_cvt_pk_bf16_f32 v125, v128, v125
	global_store_dwordx4 v0, v[122:125], s[6:7]
	v_max_f32_e32 v117, v117, v117
.Lpad_G2_65:
	s_cbranch_execz .Lpad_G2_72
	v_max_f32_e32 v118, v118, v118
	v_mul_f32_e32 v122, v114, v114
	v_max_f32_e32 v114, v119, v119
	v_mul_f32_e32 v119, v115, v115
	v_max_f32_e32 v115, v120, v120
	v_mul_f32_e32 v120, v116, v116
	v_max_f32_e32 v116, v121, v121
.Lpad_G2_66:
	s_cbranch_execz .Lpad_G2_73
	v_max_f32_e32 v114, 0, v114
	v_max_f32_e32 v115, 0, v115
	v_max_f32_e32 v116, 0, v116
	v_max_f32_e32 v117, 0, v117
	v_max_f32_e32 v106, v106, v106
	v_max_f32_e32 v118, 0, v118
	v_mul_f32_e32 v114, v114, v114
.Lpad_G2_67:
	s_cbranch_execz .Lpad_G2_74
	v_mul_f32_e32 v115, v115, v115
	v_mul_f32_e32 v116, v116, v116
	v_mul_f32_e32 v117, v117, v117
	v_max_f32_e32 v106, 0, v106
	v_max_f32_e32 v107, v107, v107
	v_max_f32_e32 v108, v108, v108
	v_lshl_add_u64 v[142:143], s[6:7], 0, v[0:1]
.Lpad_G2_68:
	s_cbranch_execz .Lpad_G2_75
	v_mul_f32_e32 v118, v118, v118
	v_cvt_pk_bf16_f32 v114, v118, v114
	v_cvt_pk_bf16_f32 v115, v115, v116
	v_cvt_pk_bf16_f32 v116, v122, v119
	v_cvt_pk_bf16_f32 v117, v120, v117
	global_store_dwordx4 v0, v[114:117], s[6:7] offset:256
	v_max_f32_e32 v0, v110, v110
.Lpad_G2_69:
	s_cbranch_execz .Lpad_G2_76
	v_mul_f32_e32 v110, v106, v106
	v_max_f32_e32 v106, v111, v111
	v_max_f32_e32 v107, 0, v107
	v_max_f32_e32 v108, 0, v108
	v_max_f32_e32 v0, 0, v0
	v_max_f32_e32 v106, 0, v106
	v_mul_f32_e32 v111, v107, v107
.Lpad_G2_70:
	s_cbranch_execz .Lpad_G2_77
	v_max_f32_e32 v107, v112, v112
	v_mul_f32_e32 v112, v108, v108
	v_max_f32_e32 v108, v113, v113
	v_max_f32_e32 v98, v98, v98
	v_mul_f32_e32 v0, v0, v0
	v_mul_f32_e32 v106, v106, v106
	v_max_f32_e32 v107, 0, v107
.Lpad_G2_71:
	s_cbranch_execz .Lpad_G2_78
	v_max_f32_e32 v108, 0, v108
	v_max_f32_e32 v98, 0, v98
	v_mul_f32_e32 v107, v107, v107
	v_max_f32_e32 v109, v109, v109
	v_mul_f32_e32 v108, v108, v108
	v_cvt_pk_bf16_f32 v106, v0, v106
	s_mov_b32 s6, 0x40000
.Lpad_G2_72:
	s_cbranch_execz .Lpad_G2_79
	v_max_f32_e32 v0, v102, v102
	v_mul_f32_e32 v102, v98, v98
	v_max_f32_e32 v98, v103, v103
	v_max_f32_e32 v109, 0, v109
	v_cvt_pk_bf16_f32 v107, v107, v108
	v_cvt_pk_bf16_f32 v108, v110, v111
	v_add_co_u32_e32 v110, vcc, s6, v142
.Lpad_G2_73:
	s_cbranch_execz .Lpad_G2_80
	v_max_f32_e32 v0, 0, v0
	v_max_f32_e32 v98, 0, v98
	v_max_f32_e32 v99, v99, v99
	v_max_f32_e32 v100, v100, v100
	v_max_f32_e32 v90, v90, v90
	v_mul_f32_e32 v109, v109, v109
	v_addc_co_u32_e32 v111, vcc, 0, v143, vcc
.Lpad_G2_74:
	s_cbranch_execz .Lpad_G2_81
	v_mul_f32_e32 v0, v0, v0
	v_max_f32_e32 v99, 0, v99
	v_mul_f32_e32 v98, v98, v98
	v_max_f32_e32 v100, 0, v100
	v_max_f32_e32 v90, 0, v90
	v_max_f32_e32 v91, v91, v91
	v_max_f32_e32 v92, v92, v92
.Lpad_G2_75:
	s_cbranch_execz .Lpad_G2_82
	v_cvt_pk_bf16_f32 v109, v112, v109
	global_store_dwordx4 v[110:111], v[106:109], off
	v_mul_f32_e32 v103, v99, v99
	v_max_f32_e32 v99, v104, v104
	v_mul_f32_e32 v104, v100, v100
	v_max_f32_e32 v100, v105, v105
	v_max_f32_e32 v101, v101, v101
.Lpad_G2_76:
	s_cbranch_execz .Lpad_G2_83
	v_cvt_pk_bf16_f32 v98, v0, v98
	v_max_f32_e32 v0, v94, v94
	v_mul_f32_e32 v94, v90, v90
	v_max_f32_e32 v90, v95, v95
	v_max_f32_e32 v91, 0, v91
	v_max_f32_e32 v92, 0, v92
	v_max_f32_e32 v99, 0, v99
.Lpad_G2_77:
	s_cbranch_execz .Lpad_G2_84
	v_max_f32_e32 v100, 0, v100
	v_max_f32_e32 v101, 0, v101
	v_max_f32_e32 v0, 0, v0
	v_max_f32_e32 v90, 0, v90
	v_mul_f32_e32 v95, v91, v91
	v_max_f32_e32 v91, v96, v96
	v_mul_f32_e32 v96, v92, v92
.Lpad_G2_78:
	s_cbranch_execz .Lpad_G2_85
	v_max_f32_e32 v92, v97, v97
	v_max_f32_e32 v82, v82, v82
	v_mul_f32_e32 v99, v99, v99
	v_mul_f32_e32 v100, v100, v100
	v_mul_f32_e32 v101, v101, v101
	v_mul_f32_e32 v0, v0, v0
	v_mul_f32_e32 v90, v90, v90
.Lpad_G2_79:
	s_cbranch_execz .Lpad_G2_86
	v_max_f32_e32 v91, 0, v91
	v_max_f32_e32 v92, 0, v92
	v_max_f32_e32 v82, 0, v82
	v_cvt_pk_bf16_f32 v99, v99, v100
	v_cvt_pk_bf16_f32 v100, v102, v103
	v_cvt_pk_bf16_f32 v101, v104, v101
	global_store_dwordx4 v[110:111], v[98:101], off offset:256
.Lpad_G2_80:
	s_cbranch_execz .Lpad_G2_87
	v_mul_f32_e32 v91, v91, v91
	v_max_f32_e32 v93, v93, v93
	v_mul_f32_e32 v92, v92, v92
	v_cvt_pk_bf16_f32 v90, v0, v90
	s_mov_b32 s6, 0x80000
	v_max_f32_e32 v0, v86, v86
	v_mul_f32_e32 v86, v82, v82
.Lpad_G2_81:
	s_cbranch_execz .Lpad_G2_88
	v_max_f32_e32 v82, v87, v87
	v_max_f32_e32 v93, 0, v93
	v_cvt_pk_bf16_f32 v91, v91, v92
	v_cvt_pk_bf16_f32 v92, v94, v95
	v_add_co_u32_e32 v94, vcc, s6, v142
	v_max_f32_e32 v0, 0, v0
	v_max_f32_e32 v82, 0, v82
.Lpad_G2_82:
	s_cbranch_execz .Lpad_G2_89
	v_max_f32_e32 v83, v83, v83
	v_max_f32_e32 v84, v84, v84
	v_max_f32_e32 v74, v74, v74
	v_mul_f32_e32 v93, v93, v93
	v_addc_co_u32_e32 v95, vcc, 0, v143, vcc
	v_mul_f32_e32 v0, v0, v0
	v_max_f32_e32 v83, 0, v83
.Lpad_G2_83:
	s_cbranch_execz .Lpad_G2_90
	v_mul_f32_e32 v82, v82, v82
	v_max_f32_e32 v84, 0, v84
	v_max_f32_e32 v74, 0, v74
	v_max_f32_e32 v75, v75, v75
	v_max_f32_e32 v76, v76, v76
	v_cvt_pk_bf16_f32 v93, v96, v93
	global_store_dwordx4 v[94:95], v[90:93], off
.Lpad_G2_84:
	s_cbranch_execz .Lpad_G2_91
	v_mul_f32_e32 v87, v83, v83
	v_max_f32_e32 v83, v88, v88
	v_mul_f32_e32 v88, v84, v84
	v_max_f32_e32 v84, v89, v89
	v_max_f32_e32 v85, v85, v85
	v_cvt_pk_bf16_f32 v82, v0, v82
	v_max_f32_e32 v0, v78, v78
.Lpad_G2_85:
	s_cbranch_execz .Lpad_G2_92
	v_mul_f32_e32 v78, v74, v74
	v_max_f32_e32 v74, v79, v79
	v_max_f32_e32 v75, 0, v75
	v_max_f32_e32 v76, 0, v76
	v_max_f32_e32 v83, 0, v83
	v_max_f32_e32 v84, 0, v84
	v_max_f32_e32 v85, 0, v85
.Lpad_G2_86:
	s_cbranch_execz .Lpad_G2_93
	v_max_f32_e32 v0, 0, v0
	v_max_f32_e32 v74, 0, v74
	v_mul_f32_e32 v79, v75, v75
	v_max_f32_e32 v75, v80, v80
	v_mul_f32_e32 v80, v76, v76
	v_max_f32_e32 v76, v81, v81
	v_max_f32_e32 v66, v66, v66
.Lpad_G2_87:
	s_cbranch_execz .Lpad_G2_94
	v_mul_f32_e32 v83, v83, v83
	v_mul_f32_e32 v84, v84, v84
	v_mul_f32_e32 v85, v85, v85
	v_mul_f32_e32 v0, v0, v0
	v_mul_f32_e32 v74, v74, v74
	v_max_f32_e32 v75, 0, v75
	v_max_f32_e32 v76, 0, v76
.Lpad_G2_88:
	s_cbranch_execz .Lpad_G2_95
	v_max_f32_e32 v66, 0, v66
	v_cvt_pk_bf16_f32 v83, v83, v84
	v_cvt_pk_bf16_f32 v84, v86, v87
	v_cvt_pk_bf16_f32 v85, v88, v85
	global_store_dwordx4 v[94:95], v[82:85], off offset:256
	v_mul_f32_e32 v75, v75, v75
	v_max_f32_e32 v77, v77, v77
.Lpad_G2_89:
	s_cbranch_execz .Lpad_G2_96
	v_mul_f32_e32 v76, v76, v76
	v_cvt_pk_bf16_f32 v74, v0, v74
	s_mov_b32 s6, 0xc0000
	v_max_f32_e32 v0, v70, v70
	v_mul_f32_e32 v70, v66, v66
	v_max_f32_e32 v66, v71, v71
	v_max_f32_e32 v77, 0, v77
.Lpad_G2_90:
	s_cbranch_execz .Lpad_G2_97
	v_cvt_pk_bf16_f32 v75, v75, v76
	v_cvt_pk_bf16_f32 v76, v78, v79
	v_add_co_u32_e32 v78, vcc, s6, v142
	v_max_f32_e32 v0, 0, v0
	v_max_f32_e32 v66, 0, v66
	v_max_f32_e32 v67, v67, v67
	v_max_f32_e32 v68, v68, v68
.Lpad_G2_91:
	s_cbranch_execz .Lpad_G2_98
	v_max_f32_e32 v58, v58, v58
	v_mul_f32_e32 v77, v77, v77
	v_addc_co_u32_e32 v79, vcc, 0, v143, vcc
	v_mul_f32_e32 v0, v0, v0
	v_max_f32_e32 v67, 0, v67
	v_mul_f32_e32 v66, v66, v66
	v_max_f32_e32 v68, 0, v68
.Lpad_G2_92:
	s_cbranch_execz .Lpad_G2_99
	v_max_f32_e32 v58, 0, v58
	v_max_f32_e32 v59, v59, v59
	v_max_f32_e32 v60, v60, v60
	v_cvt_pk_bf16_f32 v77, v80, v77
	global_store_dwordx4 v[78:79], v[74:77], off
	v_mul_f32_e32 v71, v67, v67
	v_max_f32_e32 v67, v72, v72
.Lpad_G2_93:
	s_cbranch_execz .Lpad_G2_100
	v_mul_f32_e32 v72, v68, v68
	v_max_f32_e32 v68, v73, v73
	v_max_f32_e32 v69, v69, v69
	v_cvt_pk_bf16_f32 v66, v0, v66
	v_max_f32_e32 v0, v62, v62
	v_mul_f32_e32 v62, v58, v58
	v_max_f32_e32 v58, v63, v63
.Lpad_G2_94:
	s_cbranch_execz .Lpad_G2_101
	v_max_f32_e32 v59, 0, v59
	v_max_f32_e32 v60, 0, v60
	v_max_f32_e32 v67, 0, v67
	v_max_f32_e32 v68, 0, v68
	v_max_f32_e32 v69, 0, v69
	v_max_f32_e32 v0, 0, v0
	v_max_f32_e32 v58, 0, v58
.Lpad_G2_95:
	s_cbranch_execz .Lpad_G2_102
	v_mul_f32_e32 v63, v59, v59
	v_max_f32_e32 v59, v64, v64
	v_mul_f32_e32 v64, v60, v60
	v_max_f32_e32 v60, v65, v65
	v_max_f32_e32 v50, v50, v50
	v_mul_f32_e32 v67, v67, v67
	v_mul_f32_e32 v68, v68, v68
.Lpad_G2_96:
	s_cbranch_execz .Lpad_G2_103
	v_mul_f32_e32 v69, v69, v69
	v_mul_f32_e32 v0, v0, v0
	v_mul_f32_e32 v58, v58, v58
	v_max_f32_e32 v59, 0, v59
	v_max_f32_e32 v60, 0, v60
	v_max_f32_e32 v50, 0, v50
	v_cvt_pk_bf16_f32 v67, v67, v68
	v_cvt_pk_bf16_f32 v68, v70, v71
	v_cvt_pk_bf16_f32 v69, v72, v69
	global_store_dwordx4 v[78:79], v[66:69], off offset:256
.Lpad_G2_97:
	s_cbranch_execz .Lpad_G2_104
	v_mul_f32_e32 v59, v59, v59
	v_max_f32_e32 v61, v61, v61
	v_mul_f32_e32 v60, v60, v60
	v_cvt_pk_bf16_f32 v58, v0, v58
	s_mov_b32 s6, 0x200000
	v_max_f32_e32 v0, v54, v54
	v_mul_f32_e32 v54, v50, v50
.Lpad_G2_98:
	s_cbranch_execz .Lpad_G2_105
	v_max_f32_e32 v50, v55, v55
	v_max_f32_e32 v61, 0, v61
	v_cvt_pk_bf16_f32 v59, v59, v60
	v_cvt_pk_bf16_f32 v60, v62, v63
	v_add_co_u32_e32 v62, vcc, s6, v142
	v_max_f32_e32 v0, 0, v0
	v_max_f32_e32 v50, 0, v50
.Lpad_G2_99:
	s_cbranch_execz .Lpad_G2_106
	v_max_f32_e32 v51, v51, v51
	v_max_f32_e32 v52, v52, v52
	v_max_f32_e32 v42, v42, v42
	v_mul_f32_e32 v61, v61, v61
	v_addc_co_u32_e32 v63, vcc, 0, v143, vcc
	v_mul_f32_e32 v0, v0, v0
	v_max_f32_e32 v51, 0, v51
.Lpad_G2_100:
	s_cbranch_execz .Lpad_G2_107
	v_mul_f32_e32 v50, v50, v50
	v_max_f32_e32 v52, 0, v52
	v_max_f32_e32 v42, 0, v42
	v_max_f32_e32 v43, v43, v43
	v_max_f32_e32 v44, v44, v44
	v_cvt_pk_bf16_f32 v61, v64, v61
	global_store_dwordx4 v[62:63], v[58:61], off
.Lpad_G2_101:
	s_cbranch_execz .Lpad_G2_108
	v_mul_f32_e32 v55, v51, v51
	v_max_f32_e32 v51, v56, v56
	v_mul_f32_e32 v56, v52, v52
	v_max_f32_e32 v52, v57, v57
	v_max_f32_e32 v53, v53, v53
	v_cvt_pk_bf16_f32 v50, v0, v50
	v_max_f32_e32 v0, v46, v46
.Lpad_G2_102:
	s_cbranch_execz .Lpad_G2_109
	v_mul_f32_e32 v46, v42, v42
	v_max_f32_e32 v42, v47, v47
	v_max_f32_e32 v43, 0, v43
	v_max_f32_e32 v44, 0, v44
	v_max_f32_e32 v51, 0, v51
	v_max_f32_e32 v52, 0, v52
	v_max_f32_e32 v53, 0, v53
.Lpad_G2_103:
	s_cbranch_execz .Lpad_G2_110
	v_max_f32_e32 v0, 0, v0
	v_max_f32_e32 v42, 0, v42
	v_mul_f32_e32 v47, v43, v43
	v_max_f32_e32 v43, v48, v48
	v_mul_f32_e32 v48, v44, v44
	v_max_f32_e32 v44, v49, v49
	v_max_f32_e32 v34, v34, v34
.Lpad_G2_104:
	s_cbranch_execz .Lpad_G2_111
	v_mul_f32_e32 v51, v51, v51
	v_mul_f32_e32 v52, v52, v52
	v_mul_f32_e32 v53, v53, v53
	v_mul_f32_e32 v0, v0, v0
	v_mul_f32_e32 v42, v42, v42
	v_max_f32_e32 v43, 0, v43
	v_max_f32_e32 v44, 0, v44
.Lpad_G2_105:
	s_cbranch_execz .Lpad_G2_112
	v_max_f32_e32 v34, 0, v34
	v_cvt_pk_bf16_f32 v51, v51, v52
	v_cvt_pk_bf16_f32 v52, v54, v55
	v_cvt_pk_bf16_f32 v53, v56, v53
	global_store_dwordx4 v[62:63], v[50:53], off offset:256
	v_mul_f32_e32 v43, v43, v43
	v_max_f32_e32 v45, v45, v45
.Lpad_G2_106:
	s_cbranch_execz .Lpad_G2_113
	v_mul_f32_e32 v44, v44, v44
	v_cvt_pk_bf16_f32 v42, v0, v42
	s_mov_b32 s6, 0x240000
	v_max_f32_e32 v0, v38, v38
	v_mul_f32_e32 v38, v34, v34
	v_max_f32_e32 v34, v39, v39
	v_max_f32_e32 v45, 0, v45
.Lpad_G2_107:
	s_cbranch_execz .Lpad_G2_114
	v_cvt_pk_bf16_f32 v43, v43, v44
	v_cvt_pk_bf16_f32 v44, v46, v47
	v_add_co_u32_e32 v46, vcc, s6, v142
	v_max_f32_e32 v0, 0, v0
	v_max_f32_e32 v34, 0, v34
	v_max_f32_e32 v35, v35, v35
	v_max_f32_e32 v36, v36, v36
.Lpad_G2_108:
	s_cbranch_execz .Lpad_G2_115
	v_max_f32_e32 v26, v26, v26
	v_mul_f32_e32 v45, v45, v45
	v_addc_co_u32_e32 v47, vcc, 0, v143, vcc
	v_mul_f32_e32 v0, v0, v0
	v_max_f32_e32 v35, 0, v35
	v_mul_f32_e32 v34, v34, v34
	v_max_f32_e32 v36, 0, v36
.Lpad_G2_109:
	s_cbranch_execz .Lpad_G2_116
	v_max_f32_e32 v26, 0, v26
	v_max_f32_e32 v27, v27, v27
	v_max_f32_e32 v28, v28, v28
	v_cvt_pk_bf16_f32 v45, v48, v45
	global_store_dwordx4 v[46:47], v[42:45], off
	v_mul_f32_e32 v39, v35, v35
	v_max_f32_e32 v35, v40, v40
.Lpad_G2_110:
	s_cbranch_execz .Lpad_G2_117
	v_mul_f32_e32 v40, v36, v36
	v_max_f32_e32 v36, v41, v41
	v_max_f32_e32 v37, v37, v37
	v_cvt_pk_bf16_f32 v34, v0, v34
	v_max_f32_e32 v0, v30, v30
	v_mul_f32_e32 v30, v26, v26
	v_max_f32_e32 v26, v31, v31
.Lpad_G2_111:
	s_cbranch_execz .Lpad_G2_118
	v_max_f32_e32 v27, 0, v27
	v_max_f32_e32 v28, 0, v28
	v_max_f32_e32 v35, 0, v35
	v_max_f32_e32 v36, 0, v36
	v_max_f32_e32 v37, 0, v37
	v_max_f32_e32 v0, 0, v0
	v_max_f32_e32 v26, 0, v26
.Lpad_G2_112:
	s_cbranch_execz .Lpad_G2_119
	v_mul_f32_e32 v31, v27, v27
	v_max_f32_e32 v27, v32, v32
	v_mul_f32_e32 v32, v28, v28
	v_max_f32_e32 v28, v33, v33
	v_max_f32_e32 v18, v18, v18
	v_mul_f32_e32 v35, v35, v35
	v_mul_f32_e32 v36, v36, v36
.Lpad_G2_113:
	s_cbranch_execz .Lpad_G2_120
	v_mul_f32_e32 v37, v37, v37
	v_mul_f32_e32 v0, v0, v0
	v_mul_f32_e32 v26, v26, v26
	v_max_f32_e32 v27, 0, v27
	v_max_f32_e32 v28, 0, v28
	v_max_f32_e32 v18, 0, v18
	v_cvt_pk_bf16_f32 v35, v35, v36
	v_cvt_pk_bf16_f32 v36, v38, v39
	v_cvt_pk_bf16_f32 v37, v40, v37
	global_store_dwordx4 v[46:47], v[34:37], off offset:256
.Lpad_G2_114:
	s_cbranch_execz .Lpad_G2_121
	v_mul_f32_e32 v27, v27, v27
	v_max_f32_e32 v29, v29, v29
	v_mul_f32_e32 v28, v28, v28
	v_cvt_pk_bf16_f32 v26, v0, v26
	s_mov_b32 s6, 0x280000
	v_max_f32_e32 v0, v22, v22
	v_mul_f32_e32 v22, v18, v18
.Lpad_G2_115:
	s_cbranch_execz .Lpad_G2_122
	v_max_f32_e32 v18, v23, v23
	v_max_f32_e32 v29, 0, v29
	v_cvt_pk_bf16_f32 v27, v27, v28
	v_cvt_pk_bf16_f32 v28, v30, v31
	v_add_co_u32_e32 v30, vcc, s6, v142
	v_max_f32_e32 v0, 0, v0
	v_max_f32_e32 v18, 0, v18
.Lpad_G2_116:
	s_cbranch_execz .Lpad_G2_123
	v_max_f32_e32 v19, v19, v19
	v_max_f32_e32 v20, v20, v20
	v_max_f32_e32 v10, v10, v10
	v_max_f32_e32 v11, v11, v11
	v_max_f32_e32 v12, v12, v12
	v_mul_f32_e32 v29, v29, v29
	v_addc_co_u32_e32 v31, vcc, 0, v143, vcc
.Lpad_G2_117:
	s_cbranch_execz .Lpad_G2_124
	v_mul_f32_e32 v0, v0, v0
	v_max_f32_e32 v19, 0, v19
	v_mul_f32_e32 v18, v18, v18
	v_max_f32_e32 v20, 0, v20
	v_max_f32_e32 v10, 0, v10
	v_max_f32_e32 v11, 0, v11
	v_max_f32_e32 v12, 0, v12
.Lpad_G2_118:
	s_cbranch_execz .Lpad_G2_125
	v_cvt_pk_bf16_f32 v29, v32, v29
	global_store_dwordx4 v[30:31], v[26:29], off
	v_mul_f32_e32 v23, v19, v19
	v_max_f32_e32 v19, v24, v24
	v_mul_f32_e32 v24, v20, v20
	v_max_f32_e32 v20, v25, v25
	v_max_f32_e32 v21, v21, v21
.Lpad_G2_119:
	s_cbranch_execz .Lpad_G2_126
	v_cvt_pk_bf16_f32 v18, v0, v18
	v_max_f32_e32 v0, v14, v14
	v_mul_f32_e32 v14, v10, v10
	v_max_f32_e32 v10, v15, v15
	v_mul_f32_e32 v15, v11, v11
	v_max_f32_e32 v11, v16, v16
	v_mul_f32_e32 v16, v12, v12
.Lpad_G2_120:
	s_cbranch_execz .Lpad_G2_127
	v_max_f32_e32 v12, v17, v17
	v_max_f32_e32 v19, 0, v19
	v_max_f32_e32 v20, 0, v20
	v_max_f32_e32 v21, 0, v21
	v_max_f32_e32 v0, 0, v0
	v_max_f32_e32 v10, 0, v10
	v_max_f32_e32 v11, 0, v11
.Lpad_G2_121:
	s_cbranch_execz .Lpad_G2_128
	v_max_f32_e32 v12, 0, v12
	v_max_f32_e32 v2, v2, v2
	v_max_f32_e32 v3, v3, v3
	v_max_f32_e32 v4, v4, v4
	v_mul_f32_e32 v19, v19, v19
	v_mul_f32_e32 v20, v20, v20
	v_mul_f32_e32 v21, v21, v21
.Lpad_G2_122:
	s_cbranch_execz .Lpad_G2_129
	v_mul_f32_e32 v0, v0, v0
	v_mul_f32_e32 v10, v10, v10
	v_mul_f32_e32 v11, v11, v11
	v_mul_f32_e32 v12, v12, v12
	s_mov_b32 s6, 0x2c0000
	v_max_f32_e32 v2, 0, v2
	v_max_f32_e32 v3, 0, v3
.Lpad_G2_123:
	s_cbranch_execz .Lwalk_done
	v_max_f32_e32 v4, 0, v4
	v_cvt_pk_bf16_f32 v19, v19, v20
	v_cvt_pk_bf16_f32 v20, v22, v23
	v_cvt_pk_bf16_f32 v21, v24, v21
	global_store_dwordx4 v[30:31], v[18:21], off offset:256
	v_max_f32_e32 v13, v13, v13
	v_cvt_pk_bf16_f32 v10, v0, v10
	v_cvt_pk_bf16_f32 v11, v11, v12
	v_cvt_pk_bf16_f32 v12, v14, v15
	v_add_co_u32_e32 v14, vcc, s6, v142
.Lpad_G2_124:
	s_cbranch_execz .Lwalk_done
	v_max_f32_e32 v0, v6, v6
	v_mul_f32_e32 v6, v2, v2
	v_max_f32_e32 v2, v7, v7
	v_mul_f32_e32 v7, v3, v3
	v_max_f32_e32 v3, v8, v8
	v_mul_f32_e32 v8, v4, v4
	v_max_f32_e32 v4, v9, v9
.Lpad_G2_125:
	s_cbranch_execz .Lwalk_done
	v_max_f32_e32 v5, v5, v5
	v_max_f32_e32 v13, 0, v13
	v_addc_co_u32_e32 v15, vcc, 0, v143, vcc
	v_max_f32_e32 v2, 0, v2
	v_max_f32_e32 v3, 0, v3
	v_max_f32_e32 v4, 0, v4
	v_max_f32_e32 v5, 0, v5
.Lpad_G2_126:
	s_cbranch_execz .Lwalk_done
	v_mul_f32_e32 v13, v13, v13
	v_max_f32_e32 v0, 0, v0
	v_mul_f32_e32 v2, v2, v2
	v_mul_f32_e32 v3, v3, v3
	v_mul_f32_e32 v4, v4, v4
	v_mul_f32_e32 v5, v5, v5
	s_andn2_b64 vcc, exec, s[40:41]
.Lpad_G2_127:
	s_cbranch_execz .Lwalk_done
	s_mov_b64 s[6:7], -1
	s_mov_b32 s70, 0x2aaaaaab
	s_mov_b64 s[72:73], 0x26000
	v_cvt_pk_bf16_f32 v13, v16, v13
	global_store_dwordx4 v[14:15], v[10:13], off
	v_mul_f32_e32 v0, v0, v0
	v_cvt_pk_bf16_f32 v2, v0, v2
	v_cvt_pk_bf16_f32 v3, v3, v4
	v_cvt_pk_bf16_f32 v4, v6, v7
	v_cvt_pk_bf16_f32 v5, v8, v5
	global_store_dwordx4 v[14:15], v[2:5], off offset:256
.Lpad_G2_128:
	s_cbranch_execz .Lwalk_done
	s_cbranch_vccnz .LBB0_28
	s_andn2_b64 vcc, exec, s[28:29]
	s_cbranch_vccnz .LBB0_27
	s_barrier
	s_branch .LBB0_27

.Lpad_G2_129:
	s_cbranch_execz .Lwalk_done
	s_barrier
	v_readlane_b32 s58, v254, 60
	s_mov_b32 s59, 0xc000
	v_readlane_b32 s21, v252, 1
	v_readlane_b32 s63, v254, 58

.Lpad_GM_0:
	s_cbranch_execz .Lpad_GM_7
	v_mul_i32_i24_e32 v4, 0x400, v3
	v_sub_u32_e32 v2, v2, v4
	v_lshrrev_b32_e32 v4, 4, v2
	v_bitop3_b32 v4, v4, v2, 32 bitop3:0x6c
	s_add_u32 s18, s60, 0x28700000
	v_ashrrev_i32_e32 v2, 31, v4
	s_addc_u32 s19, s61, 0
.Lpad_GM_1:
	s_cbranch_execz .Lpad_GM_8
	s_lshl_b64 s[8:9], s[4:5], 19
	v_lshrrev_b32_e32 v2, 26, v2
	s_add_u32 s7, s60, s8
	v_add_u32_e32 v6, v4, v2
	v_lshlrev_b32_e32 v7, 3, v3
	s_addc_u32 s8, s61, s9
	v_ashrrev_i32_e32 v2, 6, v6
.Lpad_GM_2:
	s_cbranch_execz .Lpad_GM_9
	v_and_b32_e32 v7, -16, v7
	s_add_u32 s20, s7, 0xb800000
	v_add_u32_e32 v7, v2, v7
	s_addc_u32 s21, s8, 0
	v_and_b32_e32 v2, 3, v2
	s_mov_b32 s8, 0x7fffffe0
	v_lshrrev_b32_e32 v8, 2, v7
.Lpad_GM_3:
	s_cbranch_execz .Lpad_GM_10
	v_lshlrev_b32_e32 v9, 1, v7
	v_and_or_b32 v2, v7, s8, v2
	v_and_b32_e32 v8, 4, v8
	v_and_b32_e32 v9, 24, v9
	v_or3_b32 v2, v2, v8, v9
	v_mul_lo_u32 v8, v2, s6
	v_lshlrev_b32_e32 v2, 5, v3
.Lpad_GM_4:
	s_cbranch_execz .Lpad_GM_11
	v_and_b32_e32 v3, 0xc0, v6
	v_sub_u32_e32 v3, v4, v3
	v_ashrrev_i16_sdwa v3, v225, sext(v3) dst_sel:DWORD dst_unused:UNUSED_PAD src0_sel:DWORD src1_sel:BYTE_0
	v_and_b32_e32 v2, 32, v2
	v_bfe_i32 v3, v3, 0, 16
	v_add_u32_e32 v6, v2, v3
	v_mul_lo_u32 v4, v7, s6
.Lpad_GM_5:
	s_cbranch_execz .Lpad_GM_12
	v_add_lshl_u32 v130, v8, v6, 1
	v_add_lshl_u32 v132, v6, v4, 1
	v_bfe_i32 v6, v0, 27, 1
	v_lshrrev_b32_e32 v6, 22, v6
	v_add_u32_e32 v6, v5, v6
	v_and_b32_e32 v6, 0xfffffc00, v6
	v_sub_u32_e32 v5, v5, v6
.Lpad_GM_6:
	s_cbranch_execz .Lpad_GM_13
	v_lshrrev_b32_e32 v6, 4, v5
	v_ashrrev_i32_e32 v8, 31, v0
	v_bitop3_b32 v6, v6, v5, 32 bitop3:0x6c
	v_lshrrev_b32_e32 v8, 26, v8
	v_ashrrev_i32_e32 v5, 31, v6
	v_add_u32_e32 v8, v0, v8
	v_lshrrev_b32_e32 v5, 26, v5
.Lpad_GM_7:
	s_cbranch_execz .Lpad_GM_14
	v_ashrrev_i32_e32 v8, 6, v8
	v_add_u32_e32 v7, v6, v5
	v_lshlrev_b32_e32 v9, 3, v8
	v_ashrrev_i32_e32 v5, 6, v7
	v_and_b32_e32 v9, -16, v9
	s_ashr_i32 s7, s6, 31
	v_add_u32_e32 v9, v5, v9
.Lpad_GM_8:
	s_cbranch_execz .Lpad_GM_15
	v_and_b32_e32 v5, 3, v5
	s_lshl_b64 s[44:45], s[6:7], 9
	v_and_or_b32 v5, v9, s8, v5
	v_readlane_b32 s8, v254, 35
	v_readlane_b32 s11, v254, 34
	s_mul_i32 s8, s44, s8
	s_mul_hi_u32 s9, s44, s11
.Lpad_GM_9:
	s_cbranch_execz .Lpad_GM_16
	s_add_i32 s10, s9, s8
	s_lshr_b64 s[8:9], s[6:7], 23
	v_readlane_b32 s12, v254, 32
	v_lshrrev_b32_e32 v10, 2, v9
	v_lshlrev_b32_e32 v11, 1, v9
	s_mul_i32 s9, s8, s11
	v_readlane_b32 s13, v254, 33
.Lpad_GM_10:
	s_cbranch_execz .Lpad_GM_17
	v_and_b32_e32 v10, 4, v10
	v_and_b32_e32 v11, 24, v11
	v_and_b32_e32 v7, 0xc0, v7
	s_add_i32 s9, s10, s9
	s_mul_i32 s17, s44, s11
	s_mul_i32 s10, s44, s13
	s_mul_hi_u32 s11, s44, s12
.Lpad_GM_11:
	s_cbranch_execz .Lpad_GM_18
	s_ashr_i32 s16, s14, 6
	v_or3_b32 v5, v5, v10, v11
	v_sub_u32_e32 v6, v6, v7
	s_add_i32 s10, s11, s10
	s_mul_i32 s8, s8, s12
	s_ashr_i32 s15, s14, 8
	s_lshl_b64 s[28:29], s[6:7], 8
.Lpad_GM_12:
	s_cbranch_execz .Lpad_GM_19
	s_lshl_b32 s49, s16, 10
	v_mul_lo_u32 v10, v5, s6
	v_lshlrev_b32_e32 v5, 5, v8
	v_ashrrev_i16_sdwa v6, v225, sext(v6) dst_sel:DWORD dst_unused:UNUSED_PAD src0_sel:DWORD src1_sel:BYTE_0
	s_add_i32 s8, s10, s8
	s_mul_i32 s10, s44, s12
	v_and_b32_e32 v5, 32, v5
.Lpad_GM_13:
	s_cbranch_execz .Lpad_GM_20
	v_bfe_i32 v6, v6, 0, 16
	s_add_u32 s10, s20, s10
	v_add_u32_e32 v8, v5, v6
	s_addc_u32 s11, s21, s8
	s_add_i32 s58, s49, 0
	v_add_lshl_u32 v134, v10, v8, 1
	s_add_i32 m0, s58, 0x10000
.Lpad_GM_14:
	s_cbranch_execz .Lpad_GM_21
	v_mul_lo_u32 v7, v9, s6
	global_load_lds_dwordx4 v134, s[10:11]
	s_add_i32 m0, s58, 0x12000
	s_add_u32 s12, s10, s28
	global_load_lds_dwordx4 v130, s[10:11]
	s_addc_u32 s13, s11, s29
	s_add_i32 m0, s58, 0x14000
.Lpad_GM_15:
	s_cbranch_execz .Lpad_GM_22
	v_add_lshl_u32 v136, v8, v7, 1
	global_load_lds_dwordx4 v134, s[12:13]
	s_add_i32 m0, s58, 0x16000
	s_add_u32 s8, s18, s17
	s_addc_u32 s9, s19, s9
	s_add_i32 s59, s58, 0x2000
	global_load_lds_dwordx4 v130, s[12:13]
.Lpad_GM_16:
	s_cbranch_execz .Lpad_GM_23
	s_mov_b32 m0, s58
	s_add_u32 s40, s8, s28
	global_load_lds_dwordx4 v136, s[8:9]
	s_mov_b32 m0, s59
	s_addc_u32 s41, s9, s29
	s_add_i32 s62, s58, 0x4000
	global_load_lds_dwordx4 v132, s[8:9]
.Lpad_GM_17:
	s_cbranch_execz .Lpad_GM_24
	s_mov_b32 m0, s62
	s_add_i32 s63, s58, 0x6000
	global_load_lds_dwordx4 v136, s[40:41]
	s_mov_b32 m0, s63
	s_cmp_eq_u32 s15, 1
	global_load_lds_dwordx4 v132, s[40:41]
	s_cselect_b64 s[46:47], -1, 0
.Lpad_GM_18:
	s_cbranch_execz .Lpad_GM_25
	s_cmp_lg_u32 s15, 1
	s_cbranch_scc1 .LBB0_166
	s_barrier

.Lpad_GM_19:
	s_cbranch_execz .Lpad_GM_26
	v_mov_b32_e32 v137, v1
	s_add_i32 m0, s58, 0x18000
	v_lshl_add_u64 v[8:9], v[8:9], 0, s[34:35]
	v_lshl_add_u64 v[16:17], s[8:9], 0, v[136:137]
	v_mov_b32_e32 v133, v1
	s_waitcnt vmcnt(2)
	s_barrier
.Lpad_GM_20:
	s_cbranch_execz .Lpad_GM_27
	global_load_lds_dwordx4 v[8:9], off
	v_lshl_add_u64 v[8:9], v[10:11], 0, s[34:35]
	s_add_i32 m0, s58, 0x1a000
	s_add_i32 s66, s58, 0x8000
	v_lshl_add_u64 v[18:19], s[8:9], 0, v[132:133]
	global_load_lds_dwordx4 v[8:9], off
	v_lshl_add_u64 v[8:9], v[16:17], 0, s[34:35]
.Lpad_GM_21:
	s_cbranch_execz .Lpad_GM_28
	s_mov_b32 m0, s66
	s_add_i32 s67, s58, 0xa000
	v_lshl_add_u64 v[12:13], s[12:13], 0, v[134:135]
	global_load_lds_dwordx4 v[8:9], off
	v_lshl_add_u64 v[8:9], v[18:19], 0, s[34:35]
	s_mov_b32 m0, s67
	v_lshl_add_u64 v[14:15], s[12:13], 0, v[130:131]
.Lpad_GM_22:
	s_cbranch_execz .Lpad_GM_29
	global_load_lds_dwordx4 v[8:9], off
	s_add_i32 m0, s58, 0x1c000
	v_lshl_add_u64 v[8:9], v[12:13], 0, s[34:35]
	global_load_lds_dwordx4 v[8:9], off
	v_lshl_add_u64 v[8:9], v[14:15], 0, s[34:35]
	s_add_i32 m0, s58, 0x1e000
	v_and_b32_e32 v20, 48, v0
.Lpad_GM_23:
	s_cbranch_execz .Lpad_GM_30
	global_load_lds_dwordx4 v[8:9], off
	s_lshr_b32 s7, s7, 26
	v_lshlrev_b32_e32 v21, 6, v0
	s_movk_i32 s13, 0x3c0
	s_add_i32 s7, s6, s7
	v_and_or_b32 v20, v21, s13, v20
	v_lshlrev_b32_e32 v21, 2, v0
.Lpad_GM_24:
	s_cbranch_execz .Lpad_GM_31
	s_and_b32 s12, s16, 3
	s_ashr_i32 s64, s7, 6
	s_lshl_b32 s7, s15, 13
	v_and_b32_e32 v21, 32, v21
	s_lshl_b32 s65, s15, 6
	v_bitop3_b32 v22, v20, s7, v21 bitop3:0xde
	s_lshl_b32 s7, s12, 12
.Lpad_GM_25:
	s_cbranch_execz .Lpad_GM_32
	v_and_b32_e32 v143, 63, v0
	v_add_u32_e32 v0, v7, v5
	s_cmp_gt_i32 s6, 63
	v_add_lshl_u32 v0, v0, v6, 1
	s_waitcnt vmcnt(6)
	s_cselect_b64 s[52:53], -1, 0
	s_add_i32 s68, s64, -2
.Lpad_GM_26:
	s_cbranch_execz .Lpad_GM_33
	v_lshl_add_u64 v[138:139], s[28:29], 0, v[0:1]
	v_add_u32_e32 v0, v4, v2
	s_cmpk_lt_u32 s14, 0x100
	v_add_lshl_u32 v0, v0, v3, 1
	v_bitop3_b32 v142, v20, s7, v21 bitop3:0xde
	s_cselect_b64 s[54:55], -1, 0
	s_lshl_b32 s70, s12, 6
.Lpad_GM_27:
	s_cbranch_execz .Lpad_GM_34
	v_lshl_add_u64 v[140:141], s[28:29], 0, v[0:1]
	s_mov_b32 s72, 0
	v_add_u32_e32 v144, 0, v22
	v_readlane_b32 s14, v254, 31
	v_readlane_b32 s6, v254, 34
	s_barrier
	s_branch .LBB0_169
.Lpad_GM_28:
	s_cbranch_execz .Lpad_GM_35
.LBB0_167:
	s_mov_b64 s[6:7], 0

.Lpad_GM_30:
	s_cbranch_execz .Lpad_GM_37
	s_addc_u32 s13, s7, s76
	v_mov_b64_e32 v[2:3], 0x120
	v_cmp_lt_i64_e64 s[42:43], s[12:13], v[2:3]
	v_mov_b64_e32 v[2:3], 0x11f
	v_cmp_gt_i64_e32 vcc, s[12:13], v[2:3]
	s_cbranch_vccnz .LBB0_171
	s_ashr_i32 s7, s12, 31
.Lpad_GM_31:
	s_cbranch_execz .Lpad_GM_38
	s_lshr_b32 s7, s7, 29
	s_add_i32 s7, s12, s7
	s_ashr_i32 s13, s7, 3
	s_and_b32 s7, s7, -8
	s_sub_i32 s7, s12, s7
	s_cmp_lt_i32 s7, 0
	s_cselect_b32 s12, 37, 36
.Lpad_GM_32:
	s_cbranch_execz .Lpad_GM_39
	s_mul_i32 s7, s7, s12
	s_add_i32 s7, s7, s13
	s_ashr_i32 s12, s7, 31
	s_lshr_b32 s12, s12, 28
	s_add_i32 s12, s7, s12
	s_ashr_i32 s13, s12, 4
	s_lshl_b32 s13, s13, 2
.Lpad_GM_33:
	s_cbranch_execz .Lpad_GM_40
	s_sub_i32 s15, 0x48, s13
	s_min_i32 s15, s15, 4
	s_abs_i32 s16, s15
	v_cvt_f32_u32_e32 v0, s16
	s_sub_i32 s38, 0, s16
	s_and_b32 s12, s12, -16
	s_sub_i32 s7, s7, s12
.Lpad_GM_34:
	s_cbranch_execz .Lpad_GM_41
	v_rcp_iflag_f32_e32 v0, v0
	s_abs_i32 s12, s7
	s_xor_b32 s17, s7, s15
	s_ashr_i32 s17, s17, 31
	v_mul_f32_e32 v0, 0x4f7ffffe, v0
	v_cvt_u32_f32_e32 v0, v0
	s_nop 0
.Lpad_GM_35:
	s_cbranch_execz .Lpad_GM_42
	v_readfirstlane_b32 s40, v0
	s_mul_i32 s38, s38, s40
	s_mul_hi_u32 s38, s40, s38
	s_add_i32 s40, s40, s38
	s_mul_hi_u32 s38, s12, s40
	s_mul_i32 s40, s38, s16
	s_sub_i32 s12, s12, s40
.Lpad_GM_36:
	s_cbranch_execz .Lpad_GM_43
	s_add_i32 s41, s38, 1
	s_sub_i32 s40, s12, s16
	s_cmp_ge_u32 s12, s16
	s_cselect_b32 s38, s41, s38
	s_cselect_b32 s12, s40, s12
	s_add_i32 s40, s38, 1
	s_cmp_ge_u32 s12, s16
.Lpad_GM_37:
	s_cbranch_execz .Lpad_GM_44
	s_cselect_b32 s12, s40, s38
	s_xor_b32 s12, s12, s17
	s_sub_i32 s73, s12, s17
	s_mul_i32 s12, s73, s15
	s_sub_i32 s7, s7, s12
	s_add_i32 s78, s13, s7

.Lpad_GM_38:
	s_cbranch_execz .Lpad_GM_45
	v_cmp_ne_u32_e64 s[40:41], 1, v0
	s_andn2_b64 vcc, exec, s[42:43]
	s_mov_b64 s[42:43], s[8:9]
	s_cbranch_vccnz .LBB0_173
	s_ashr_i32 s7, s78, 31
	s_mul_hi_u32 s12, s44, s78
	s_mul_i32 s7, s44, s7
.Lpad_GM_39:
	s_cbranch_execz .Lpad_GM_46
	s_add_i32 s7, s12, s7
	s_mul_i32 s12, s45, s78
	s_add_i32 s7, s7, s12
	s_mul_i32 s12, s44, s78
	s_add_u32 s42, s18, s12
	s_addc_u32 s43, s19, s7

.Lpad_GM_40:
	s_cbranch_execz .Lpad_GM_47
	s_mov_b64 s[56:57], s[10:11]
	s_cbranch_vccnz .LBB0_175
	s_ashr_i32 s7, s73, 31
	s_mul_hi_u32 s12, s44, s73
	s_mul_i32 s7, s44, s7
	s_add_i32 s7, s12, s7
	s_mul_i32 s12, s45, s73
.Lpad_GM_41:
	s_cbranch_execz .Lpad_GM_48
	s_add_i32 s7, s7, s12
	s_mul_i32 s12, s44, s73
	s_add_u32 s56, s20, s12
	s_addc_u32 s57, s21, s7

.Lpad_GM_42:
	s_cbranch_execz .Lpad_GM_49
	v_mov_b32_e32 v123, v125
	v_mov_b32_e32 v122, v125
	v_mov_b32_e32 v129, v125
	v_mov_b32_e32 v128, v125
	v_mov_b32_e32 v127, v125
	v_mov_b32_e32 v126, v125
	v_mov_b32_e32 v121, v125
.Lpad_GM_43:
	s_cbranch_execz .Lpad_GM_50
	v_mov_b32_e32 v120, v125
	v_mov_b32_e32 v119, v125
	v_mov_b32_e32 v118, v125
	v_mov_b32_e32 v117, v125
	v_mov_b32_e32 v116, v125
	v_mov_b32_e32 v115, v125
	v_mov_b32_e32 v114, v125
.Lpad_GM_44:
	s_cbranch_execz .Lpad_GM_51
	v_mov_b32_e32 v113, v125
	v_mov_b32_e32 v112, v125
	v_mov_b32_e32 v111, v125
	v_mov_b32_e32 v110, v125
	v_mov_b32_e32 v109, v125
	v_mov_b32_e32 v108, v125
	v_mov_b32_e32 v107, v125
.Lpad_GM_45:
	s_cbranch_execz .Lpad_GM_52
	v_mov_b32_e32 v106, v125
	v_mov_b32_e32 v105, v125
	v_mov_b32_e32 v104, v125
	v_mov_b32_e32 v103, v125
	v_mov_b32_e32 v102, v125
	v_mov_b32_e32 v101, v125
	v_mov_b32_e32 v100, v125
.Lpad_GM_46:
	s_cbranch_execz .Lpad_GM_53
	v_mov_b32_e32 v99, v125
	v_mov_b32_e32 v98, v125
	v_mov_b32_e32 v65, v125
	v_mov_b32_e32 v64, v125
	v_mov_b32_e32 v63, v125
	v_mov_b32_e32 v62, v125
	v_mov_b32_e32 v61, v125
.Lpad_GM_47:
	s_cbranch_execz .Lpad_GM_54
	v_mov_b32_e32 v60, v125
	v_mov_b32_e32 v59, v125
	v_mov_b32_e32 v58, v125
	v_mov_b32_e32 v57, v125
	v_mov_b32_e32 v56, v125
	v_mov_b32_e32 v55, v125
	v_mov_b32_e32 v54, v125
.Lpad_GM_48:
	s_cbranch_execz .Lpad_GM_55
	v_mov_b32_e32 v53, v125
	v_mov_b32_e32 v52, v125
	v_mov_b32_e32 v51, v125
	v_mov_b32_e32 v50, v125
	v_mov_b32_e32 v49, v125
	v_mov_b32_e32 v48, v125
	v_mov_b32_e32 v47, v125
.Lpad_GM_49:
	s_cbranch_execz .Lpad_GM_56
	v_mov_b32_e32 v46, v125
	v_mov_b32_e32 v45, v125
	v_mov_b32_e32 v44, v125
	v_mov_b32_e32 v43, v125
	v_mov_b32_e32 v42, v125
	v_mov_b32_e32 v41, v125
	v_mov_b32_e32 v40, v125
.Lpad_GM_50:
	s_cbranch_execz .Lpad_GM_57
	v_mov_b32_e32 v39, v125
	v_mov_b32_e32 v38, v125
	v_mov_b32_e32 v37, v125
	v_mov_b32_e32 v36, v125
	v_mov_b32_e32 v35, v125
	v_mov_b32_e32 v34, v125
	v_mov_b32_e32 v97, v125
.Lpad_GM_51:
	s_cbranch_execz .Lpad_GM_58
	v_mov_b32_e32 v96, v125
	v_mov_b32_e32 v95, v125
	v_mov_b32_e32 v94, v125
	v_mov_b32_e32 v93, v125
	v_mov_b32_e32 v92, v125
	v_mov_b32_e32 v91, v125
	v_mov_b32_e32 v90, v125
.Lpad_GM_52:
	s_cbranch_execz .Lpad_GM_59
	v_mov_b32_e32 v89, v125
	v_mov_b32_e32 v88, v125
	v_mov_b32_e32 v87, v125
	v_mov_b32_e32 v86, v125
	v_mov_b32_e32 v85, v125
	v_mov_b32_e32 v84, v125
	v_mov_b32_e32 v83, v125
.Lpad_GM_53:
	s_cbranch_execz .Lpad_GM_60
	v_mov_b32_e32 v82, v125
	v_mov_b32_e32 v81, v125
	v_mov_b32_e32 v80, v125
	v_mov_b32_e32 v79, v125
	v_mov_b32_e32 v78, v125
	v_mov_b32_e32 v77, v125
	v_mov_b32_e32 v76, v125
.Lpad_GM_54:
	s_cbranch_execz .Lpad_GM_61
	v_mov_b32_e32 v75, v125
	v_mov_b32_e32 v74, v125
	v_mov_b32_e32 v73, v125
	v_mov_b32_e32 v72, v125
	v_mov_b32_e32 v71, v125
	v_mov_b32_e32 v70, v125
	v_mov_b32_e32 v69, v125
.Lpad_GM_55:
	s_cbranch_execz .Lpad_GM_62
	v_mov_b32_e32 v68, v125
	v_mov_b32_e32 v67, v125
	v_mov_b32_e32 v66, v125
	v_mov_b32_e32 v33, v125
	v_mov_b32_e32 v32, v125
	v_mov_b32_e32 v31, v125
	v_mov_b32_e32 v30, v125
.Lpad_GM_56:
	s_cbranch_execz .Lpad_GM_63
	v_mov_b32_e32 v29, v125
	v_mov_b32_e32 v28, v125
	v_mov_b32_e32 v27, v125
	v_mov_b32_e32 v26, v125
	v_mov_b32_e32 v25, v125
	v_mov_b32_e32 v24, v125
	v_mov_b32_e32 v23, v125
.Lpad_GM_57:
	s_cbranch_execz .Lpad_GM_64
	v_mov_b32_e32 v22, v125
	v_mov_b32_e32 v21, v125
	v_mov_b32_e32 v20, v125
	v_mov_b32_e32 v19, v125
	v_mov_b32_e32 v18, v125
	v_mov_b32_e32 v17, v125
	v_mov_b32_e32 v16, v125
.Lpad_GM_58:
	s_cbranch_execz .Lpad_GM_65
	v_mov_b32_e32 v15, v125
	v_mov_b32_e32 v14, v125
	v_mov_b32_e32 v13, v125
	v_mov_b32_e32 v12, v125
	v_mov_b32_e32 v11, v125
	v_mov_b32_e32 v10, v125
	v_mov_b32_e32 v9, v125
.Lpad_GM_59:
	s_cbranch_execz .Lpad_GM_66
	v_mov_b32_e32 v8, v125
	v_mov_b32_e32 v7, v125
	v_mov_b32_e32 v6, v125
	v_mov_b32_e32 v5, v125
	v_mov_b32_e32 v4, v125
	v_mov_b32_e32 v3, v125
	v_mov_b32_e32 v2, v125
.Lpad_GM_60:
	s_cbranch_execz .Lpad_GM_67
	s_cbranch_vccnz .LBB0_178
	s_add_u32 s8, s8, 0x80
	s_addc_u32 s9, s9, 0
	s_add_u32 s7, s10, 0x100
	v_mov_b32_e32 v2, 0
	s_addc_u32 s12, s11, 0
	s_mov_b32 s10, 0
.Lpad_GM_61:
	s_cbranch_execz .Lpad_GM_68
	v_mov_b32_e32 v3, v2
	v_mov_b32_e32 v4, v2
	v_mov_b32_e32 v5, v2
	v_mov_b32_e32 v6, v2
	v_mov_b32_e32 v7, v2
	v_mov_b32_e32 v8, v2
	v_mov_b32_e32 v9, v2
.Lpad_GM_62:
	s_cbranch_execz .Lpad_GM_69
	v_mov_b32_e32 v10, v2
	v_mov_b32_e32 v11, v2
	v_mov_b32_e32 v12, v2
	v_mov_b32_e32 v13, v2
	v_mov_b32_e32 v14, v2
	v_mov_b32_e32 v15, v2
	v_mov_b32_e32 v16, v2
.Lpad_GM_63:
	s_cbranch_execz .Lpad_GM_70
	v_mov_b32_e32 v17, v2
	v_mov_b32_e32 v18, v2
	v_mov_b32_e32 v19, v2
	v_mov_b32_e32 v20, v2
	v_mov_b32_e32 v21, v2
	v_mov_b32_e32 v22, v2
	v_mov_b32_e32 v23, v2
.Lpad_GM_64:
	s_cbranch_execz .Lpad_GM_71
	v_mov_b32_e32 v24, v2
	v_mov_b32_e32 v25, v2
	v_mov_b32_e32 v26, v2
	v_mov_b32_e32 v27, v2
	v_mov_b32_e32 v28, v2
	v_mov_b32_e32 v29, v2
	v_mov_b32_e32 v30, v2
.Lpad_GM_65:
	s_cbranch_execz .Lpad_GM_72
	v_mov_b32_e32 v31, v2
	v_mov_b32_e32 v32, v2
	v_mov_b32_e32 v33, v2
	v_mov_b32_e32 v66, v2
	v_mov_b32_e32 v67, v2
	v_mov_b32_e32 v68, v2
	v_mov_b32_e32 v69, v2
.Lpad_GM_66:
	s_cbranch_execz .Lpad_GM_73
	v_mov_b32_e32 v70, v2
	v_mov_b32_e32 v71, v2
	v_mov_b32_e32 v72, v2
	v_mov_b32_e32 v73, v2
	v_mov_b32_e32 v74, v2
	v_mov_b32_e32 v75, v2
	v_mov_b32_e32 v76, v2
.Lpad_GM_67:
	s_cbranch_execz .Lpad_GM_74
	v_mov_b32_e32 v77, v2
	v_mov_b32_e32 v78, v2
	v_mov_b32_e32 v79, v2
	v_mov_b32_e32 v80, v2
	v_mov_b32_e32 v81, v2
	v_mov_b32_e32 v82, v2
	v_mov_b32_e32 v83, v2
.Lpad_GM_68:
	s_cbranch_execz .Lpad_GM_75
	v_mov_b32_e32 v84, v2
	v_mov_b32_e32 v85, v2
	v_mov_b32_e32 v86, v2
	v_mov_b32_e32 v87, v2
	v_mov_b32_e32 v88, v2
	v_mov_b32_e32 v89, v2
	v_mov_b32_e32 v90, v2
.Lpad_GM_69:
	s_cbranch_execz .Lpad_GM_76
	v_mov_b32_e32 v91, v2
	v_mov_b32_e32 v92, v2
	v_mov_b32_e32 v93, v2
	v_mov_b32_e32 v94, v2
	v_mov_b32_e32 v95, v2
	v_mov_b32_e32 v96, v2
	v_mov_b32_e32 v97, v2
.Lpad_GM_70:
	s_cbranch_execz .Lpad_GM_77
	v_mov_b32_e32 v34, v2
	v_mov_b32_e32 v35, v2
	v_mov_b32_e32 v36, v2
	v_mov_b32_e32 v37, v2
	v_mov_b32_e32 v38, v2
	v_mov_b32_e32 v39, v2
	v_mov_b32_e32 v40, v2
.Lpad_GM_71:
	s_cbranch_execz .Lpad_GM_78
	v_mov_b32_e32 v41, v2
	v_mov_b32_e32 v42, v2
	v_mov_b32_e32 v43, v2
	v_mov_b32_e32 v44, v2
	v_mov_b32_e32 v45, v2
	v_mov_b32_e32 v46, v2
	v_mov_b32_e32 v47, v2
.Lpad_GM_72:
	s_cbranch_execz .Lpad_GM_79
	v_mov_b32_e32 v48, v2
	v_mov_b32_e32 v49, v2
	v_mov_b32_e32 v50, v2
	v_mov_b32_e32 v51, v2
	v_mov_b32_e32 v52, v2
	v_mov_b32_e32 v53, v2
	v_mov_b32_e32 v54, v2
.Lpad_GM_73:
	s_cbranch_execz .Lpad_GM_80
	v_mov_b32_e32 v55, v2
	v_mov_b32_e32 v56, v2
	v_mov_b32_e32 v57, v2
	v_mov_b32_e32 v58, v2
	v_mov_b32_e32 v59, v2
	v_mov_b32_e32 v60, v2
	v_mov_b32_e32 v61, v2
.Lpad_GM_74:
	s_cbranch_execz .Lpad_GM_81
	v_mov_b32_e32 v62, v2
	v_mov_b32_e32 v63, v2
	v_mov_b32_e32 v64, v2
	v_mov_b32_e32 v65, v2
	v_mov_b32_e32 v98, v2
	v_mov_b32_e32 v99, v2
	v_mov_b32_e32 v100, v2
.Lpad_GM_75:
	s_cbranch_execz .Lpad_GM_82
	v_mov_b32_e32 v101, v2
	v_mov_b32_e32 v102, v2
	v_mov_b32_e32 v103, v2
	v_mov_b32_e32 v104, v2
	v_mov_b32_e32 v105, v2
	v_mov_b32_e32 v106, v2
	v_mov_b32_e32 v107, v2
.Lpad_GM_76:
	s_cbranch_execz .Lpad_GM_83
	v_mov_b32_e32 v108, v2
	v_mov_b32_e32 v109, v2
	v_mov_b32_e32 v110, v2
	v_mov_b32_e32 v111, v2
	v_mov_b32_e32 v112, v2
	v_mov_b32_e32 v113, v2
	v_mov_b32_e32 v114, v2

.Lpad_GM_78:
	s_cbranch_execz .Lpad_GM_85
	v_mov_b32_e32 v126, v2
	v_mov_b32_e32 v127, v2
	v_mov_b32_e32 v128, v2
	v_mov_b32_e32 v129, v2
	v_mov_b32_e32 v122, v2
	v_mov_b32_e32 v123, v2
	v_mov_b32_e32 v124, v2
.Lpad_GM_79:
	s_cbranch_execz .Lpad_GM_86
	v_mov_b32_e32 v125, v2

.Lpad_GM_80:
	s_cbranch_execz .Lpad_GM_87
	s_cmp_lt_u32 s14, 2
	s_movk_i32 s9, 0x80
	s_cselect_b32 s79, 0xc0, s9
	s_mov_b32 s9, 0x25a00000
	s_cselect_b32 s9, s9, 0x27500000
	s_add_u32 s86, s60, s9
	s_addc_u32 s87, s61, 0
.Lpad_GM_81:
	s_cbranch_execz .Lpad_GM_88
	s_mul_i32 s88, s8, 0x4800
	s_add_u32 s8, s6, s88
	s_addc_u32 s9, s7, 0
	v_mov_b32_e32 v0, v143
	s_mul_i32 s9, s9, s79
	s_mul_hi_u32 s10, s8, s79
	s_add_i32 s9, s10, s9
.Lpad_GM_82:
	s_cbranch_execz .Lpad_GM_89
	v_and_or_b32 v145, v0, 15, s65
	s_mul_i32 s8, s8, s79
	v_mul_lo_u32 v145, s79, v145
	s_lshl_b64 s[8:9], s[8:9], 1
	v_lshlrev_b32_e32 v145, 1, v145
	v_and_b32_e32 v0, -16, v0
	s_add_u32 s8, s86, s8
.Lpad_GM_83:
	s_cbranch_execz .Lpad_GM_90
	v_add3_u32 v0, v0, s70, v145
	s_addc_u32 s9, s87, s9
	v_lshl_add_u64 v[146:147], s[8:9], 0, v[0:1]
	v_cvt_pk_bf16_f32 v122, v122, v123
	v_cvt_pk_bf16_f32 v123, v124, v125
	v_cvt_pk_bf16_f32 v124, v126, v127
	v_cvt_pk_bf16_f32 v125, v128, v129
	global_store_dwordx4 v0, v[122:125], s[8:9]
.Lpad_GM_84:
	s_cbranch_execz .Lpad_GM_91
	s_lshl_b32 s38, s79, 5
	s_lshl_b32 s8, s79, 6
	s_lshl_b32 s12, s79, 8
	s_addk_i32 s88, 0x4800
	v_cvt_pk_bf16_f32 v118, v118, v119
	v_cvt_pk_bf16_f32 v119, v120, v121
	v_cvt_pk_bf16_f32 v120, v114, v115
	v_lshl_add_u64 v[114:115], v[146:147], 0, s[38:39]
.Lpad_GM_85:
	s_cbranch_execz .Lpad_GM_92
	s_mov_b32 s9, s39
	s_add_u32 s6, s6, s88
	v_cvt_pk_bf16_f32 v121, v116, v117
	global_store_dwordx4 v[114:115], v[118:121], off
	v_cvt_pk_bf16_f32 v110, v110, v111
	v_cvt_pk_bf16_f32 v111, v112, v113
	v_cvt_pk_bf16_f32 v112, v106, v107
	v_lshl_add_u64 v[106:107], v[146:147], 0, s[8:9]
.Lpad_GM_86:
	s_cbranch_execz .Lpad_GM_93
	s_mul_i32 s10, s79, 0x60
	s_mov_b32 s11, s39
	s_addc_u32 s7, s7, 0
	v_cvt_pk_bf16_f32 v113, v108, v109
	global_store_dwordx4 v[106:107], v[110:113], off
	v_cvt_pk_bf16_f32 v102, v102, v103
	v_cvt_pk_bf16_f32 v103, v104, v105
	v_cvt_pk_bf16_f32 v104, v98, v99
	v_lshl_add_u64 v[98:99], v[146:147], 0, s[10:11]
.Lpad_GM_87:
	s_cbranch_execz .Lpad_GM_94
	s_mov_b32 s13, s39
	s_mul_i32 s7, s7, s79
	s_mul_hi_u32 s88, s6, s79
	v_cvt_pk_bf16_f32 v105, v100, v101
	global_store_dwordx4 v[98:99], v[102:105], off
	v_cvt_pk_bf16_f32 v94, v94, v95
	v_cvt_pk_bf16_f32 v95, v96, v97
	v_cvt_pk_bf16_f32 v96, v90, v91
	v_lshl_add_u64 v[90:91], v[146:147], 0, s[12:13]
.Lpad_GM_88:
	s_cbranch_execz .Lpad_GM_95
	s_mul_i32 s14, s79, 0x120
	s_mov_b32 s15, s39
	s_add_i32 s7, s88, s7
	s_mul_i32 s6, s6, s79
	v_cvt_pk_bf16_f32 v97, v92, v93
	global_store_dwordx4 v[90:91], v[94:97], off
	v_cvt_pk_bf16_f32 v86, v86, v87
	v_cvt_pk_bf16_f32 v87, v88, v89
	v_cvt_pk_bf16_f32 v88, v82, v83
	v_lshl_add_u64 v[82:83], v[146:147], 0, s[14:15]
.Lpad_GM_89:
	s_cbranch_execz .Lpad_GM_96
	s_mul_i32 s16, s79, 0x140
	s_mov_b32 s17, s39
	s_lshl_b64 s[6:7], s[6:7], 1
	v_cvt_pk_bf16_f32 v89, v84, v85
	global_store_dwordx4 v[82:83], v[86:89], off
	v_cvt_pk_bf16_f32 v78, v78, v79
	v_cvt_pk_bf16_f32 v79, v80, v81
	v_cvt_pk_bf16_f32 v80, v74, v75
	v_lshl_add_u64 v[74:75], v[146:147], 0, s[16:17]
.Lpad_GM_90:
	s_cbranch_execz .Lpad_GM_97
	s_mul_i32 s84, s79, 0x160
	s_mov_b32 s85, s39
	s_add_u32 s6, s86, s6
	v_cvt_pk_bf16_f32 v81, v76, v77
	global_store_dwordx4 v[74:75], v[78:81], off
	v_cvt_pk_bf16_f32 v70, v70, v71
	v_cvt_pk_bf16_f32 v71, v72, v73
	v_cvt_pk_bf16_f32 v72, v66, v67
	v_lshl_add_u64 v[66:67], v[146:147], 0, s[84:85]
.Lpad_GM_91:
	s_cbranch_execz .Lpad_GM_98
	s_addc_u32 s7, s87, s7
	v_cvt_pk_bf16_f32 v73, v68, v69
	global_store_dwordx4 v[66:67], v[70:73], off
	v_lshl_add_u64 v[66:67], s[6:7], 0, v[0:1]
	v_cvt_pk_bf16_f32 v62, v62, v63
	v_cvt_pk_bf16_f32 v63, v64, v65
	v_cvt_pk_bf16_f32 v64, v58, v59
	v_cvt_pk_bf16_f32 v65, v60, v61
	global_store_dwordx4 v0, v[62:65], s[6:7]
.Lpad_GM_92:
	s_cbranch_execz .Lpad_GM_99
	v_cvt_pk_bf16_f32 v54, v54, v55
	v_cvt_pk_bf16_f32 v55, v56, v57
	v_cvt_pk_bf16_f32 v56, v50, v51
	v_lshl_add_u64 v[50:51], v[66:67], 0, s[38:39]
	v_cvt_pk_bf16_f32 v57, v52, v53
	global_store_dwordx4 v[50:51], v[54:57], off
	v_cvt_pk_bf16_f32 v46, v46, v47
	v_cvt_pk_bf16_f32 v47, v48, v49
	v_cvt_pk_bf16_f32 v48, v42, v43
	v_lshl_add_u64 v[42:43], v[66:67], 0, s[8:9]
.Lpad_GM_93:
	s_cbranch_execz .Lpad_GM_100
	v_cvt_pk_bf16_f32 v49, v44, v45
	global_store_dwordx4 v[42:43], v[46:49], off
	v_cvt_pk_bf16_f32 v38, v38, v39
	v_cvt_pk_bf16_f32 v39, v40, v41
	v_cvt_pk_bf16_f32 v40, v34, v35
	v_lshl_add_u64 v[34:35], v[66:67], 0, s[10:11]
	v_cvt_pk_bf16_f32 v41, v36, v37
	global_store_dwordx4 v[34:35], v[38:41], off
.Lpad_GM_94:
	s_cbranch_execz .Lwalk_done
	v_cvt_pk_bf16_f32 v30, v30, v31
	v_cvt_pk_bf16_f32 v31, v32, v33
	v_cvt_pk_bf16_f32 v32, v26, v27
	v_lshl_add_u64 v[26:27], v[66:67], 0, s[12:13]
	v_cvt_pk_bf16_f32 v33, v28, v29
	global_store_dwordx4 v[26:27], v[30:33], off
	v_cvt_pk_bf16_f32 v22, v22, v23
	v_cvt_pk_bf16_f32 v23, v24, v25
	v_cvt_pk_bf16_f32 v24, v18, v19
	v_lshl_add_u64 v[18:19], v[66:67], 0, s[14:15]
.Lpad_GM_95:
	s_cbranch_execz .Lwalk_done
	v_cvt_pk_bf16_f32 v25, v20, v21
	global_store_dwordx4 v[18:19], v[22:25], off
	v_cvt_pk_bf16_f32 v14, v14, v15
	v_cvt_pk_bf16_f32 v15, v16, v17
	v_cvt_pk_bf16_f32 v16, v10, v11
	v_lshl_add_u64 v[10:11], v[66:67], 0, s[16:17]
	v_cvt_pk_bf16_f32 v17, v12, v13
	global_store_dwordx4 v[10:11], v[14:17], off
.Lpad_GM_96:
	s_cbranch_execz .Lwalk_done
	v_cvt_pk_bf16_f32 v6, v6, v7
	v_cvt_pk_bf16_f32 v7, v8, v9
	v_cvt_pk_bf16_f32 v8, v2, v3
	v_lshl_add_u64 v[2:3], v[66:67], 0, s[84:85]
	s_and_b64 vcc, exec, s[40:41]
	s_mov_b64 s[6:7], -1
	s_mov_b32 s79, 0x24000
.Lpad_GM_97:
	s_cbranch_execz .Lwalk_done
	s_mov_b32 s84, 0x49000
	s_mov_b32 s85, 0x6d000
	v_cvt_pk_bf16_f32 v9, v4, v5
	global_store_dwordx4 v[2:3], v[6:9], off
	s_cbranch_vccnz .LBB0_168
	s_andn2_b64 vcc, exec, s[46:47]
	s_cbranch_vccnz .LBB0_167
.Lpad_GM_98:
	s_cbranch_execz .Lwalk_done
	s_barrier
	s_branch .LBB0_167

.Lpad_GM_99:
	s_cbranch_execz .Lwalk_done
	s_mov_b32 s70, 0x2aaaaaab
	s_mov_b64 s[64:65], 0x29100000
	s_mov_b64 s[66:67], 0x2000
	s_mov_b64 s[72:73], 0x26000
	v_readlane_b32 s21, v252, 1
	v_readlane_b32 s63, v254, 58
	s_barrier
.Lpad_GM_100:
	s_cbranch_execz .Lwalk_done
.LBB0_184:
	s_waitcnt vmcnt(0)
	v_cmp_eq_u32_e32 vcc, 0, v164
	s_waitcnt vmcnt(0) lgkmcnt(0)
	s_barrier
	s_and_saveexec_b64 s[6:7], vcc
	s_cbranch_execz .LBB0_187
	s_mov_b64 s[8:9], exec
	v_mbcnt_lo_u32_b32 v0, s8, 0
	buffer_wbl2 sc1
	s_waitcnt vmcnt(0)
	v_mbcnt_hi_u32_b32 v0, s9, v0
	v_cmp_eq_u32_e32 vcc, 0, v0
	s_and_b64 s[10:11], exec, vcc
	s_mov_b64 exec, s[10:11]
	s_cbranch_execz .LBB0_187
	s_lshl_b64 s[10:11], s[4:5], 2
	s_add_u32 s10, s60, s10
	s_addc_u32 s11, s61, s11
	s_bcnt1_i32_b64 s5, s[8:9]
	v_mov_b32_e32 v0, s5
	global_atomic_add v224, v0, s[10:11] offset:2112

.Lpad_G0_0:
	s_cbranch_execz .Lpad_G0_7
	v_mul_i32_i24_e32 v5, 0x400, v4
	v_sub_u32_e32 v3, v3, v5
	v_lshrrev_b32_e32 v5, 4, v3
	v_bitop3_b32 v3, v5, v3, 32 bitop3:0x6c
	v_ashrrev_i32_e32 v5, 31, v3
	v_lshrrev_b32_e32 v5, 26, v5
	v_add_u32_e32 v5, v3, v5
.Lpad_G0_1:
	s_cbranch_execz .Lpad_G0_8
	v_lshlrev_b32_e32 v7, 3, v4
	v_ashrrev_i32_e32 v6, 6, v5
	v_and_b32_e32 v7, -16, v7
	v_lshlrev_b32_e32 v4, 5, v4
	v_add_u32_e32 v7, v6, v7
	v_and_b32_e32 v14, 32, v4
	v_and_b32_e32 v4, 0xc0, v5
.Lpad_G0_2:
	s_cbranch_execz .Lpad_G0_9
	v_and_b32_e32 v6, 3, v6
	s_mov_b32 s6, 0x7fffffe0
	v_lshrrev_b32_e32 v8, 2, v7
	v_lshlrev_b32_e32 v9, 1, v7
	v_sub_u32_e32 v3, v3, v4
	v_and_or_b32 v6, v7, s6, v6
	v_and_b32_e32 v8, 4, v8
.Lpad_G0_3:
	s_cbranch_execz .Lpad_G0_10
	v_and_b32_e32 v9, 24, v9
	v_ashrrev_i16_sdwa v3, v225, sext(v3) dst_sel:DWORD dst_unused:UNUSED_PAD src0_sel:DWORD src1_sel:BYTE_0
	v_or3_b32 v6, v6, v8, v9
	v_bfe_i32 v15, v3, 0, 16
	v_mul_lo_u32 v6, v6, s12
	v_add_u32_e32 v3, v14, v15
	v_mul_lo_u32 v16, v7, s12
.Lpad_G0_4:
	s_cbranch_execz .Lpad_G0_11
	v_add_lshl_u32 v130, v6, v3, 1
	v_add_lshl_u32 v132, v3, v16, 1
	v_bfe_i32 v3, v0, 27, 1
	v_lshrrev_b32_e32 v3, 22, v3
	v_add_u32_e32 v3, v2, v3
	v_and_b32_e32 v3, 0xfffffc00, v3
	v_sub_u32_e32 v2, v2, v3
.Lpad_G0_5:
	s_cbranch_execz .Lpad_G0_12
	v_lshrrev_b32_e32 v3, 4, v2
	v_ashrrev_i32_e32 v5, 31, v0
	v_bitop3_b32 v2, v3, v2, 32 bitop3:0x6c
	v_lshrrev_b32_e32 v5, 26, v5
	v_ashrrev_i32_e32 v3, 31, v2
	v_add_u32_e32 v5, v0, v5
	v_lshrrev_b32_e32 v3, 26, v3
.Lpad_G0_6:
	s_cbranch_execz .Lpad_G0_13
	v_ashrrev_i32_e32 v5, 6, v5
	v_add_u32_e32 v3, v2, v3
	v_lshlrev_b32_e32 v6, 3, v5
	v_ashrrev_i32_e32 v4, 6, v3
	v_and_b32_e32 v6, -16, v6
	v_add_u32_e32 v6, v4, v6
	v_and_b32_e32 v3, 0xc0, v3
.Lpad_G0_7:
	s_cbranch_execz .Lpad_G0_14
	v_and_b32_e32 v4, 3, v4
	v_lshrrev_b32_e32 v7, 2, v6
	v_lshlrev_b32_e32 v8, 1, v6
	v_sub_u32_e32 v2, v2, v3
	v_and_or_b32 v4, v6, s6, v4
	v_and_b32_e32 v7, 4, v7
	v_and_b32_e32 v8, 24, v8
.Lpad_G0_8:
	s_cbranch_execz .Lpad_G0_15
	v_lshlrev_b32_e32 v5, 5, v5
	v_ashrrev_i16_sdwa v2, v225, sext(v2) dst_sel:DWORD dst_unused:UNUSED_PAD src0_sel:DWORD src1_sel:BYTE_0
	v_or3_b32 v4, v4, v7, v8
	v_and_b32_e32 v17, 32, v5
	v_bfe_i32 v18, v2, 0, 16
	s_lshr_b32 s15, s14, 6
	v_mul_lo_u32 v4, v4, s12
.Lpad_G0_9:
	s_cbranch_execz .Lpad_G0_16
	v_add_u32_e32 v2, v17, v18
	v_mul_lo_u32 v19, v6, s12
	v_add_lshl_u32 v134, v4, v2, 1
	v_add_lshl_u32 v136, v2, v19, 1
	v_cvt_f32_u32_e32 v2, s15
	s_ashr_i32 s13, s7, 6
	s_lshl_b32 s38, s12, 8
.Lpad_G0_10:
	s_cbranch_execz .Lpad_G0_17
	s_lshr_b32 s17, s14, 5
	v_rcp_iflag_f32_e32 v2, v2
	v_readlane_b32 s8, v254, 24
	s_ashr_i32 s5, s7, 8
	s_lshl_b64 s[54:55], s[38:39], 1
	v_mul_f32_e32 v2, 0x4f7ffffe, v2
	v_cvt_u32_f32_e32 v2, v2
.Lpad_G0_11:
	s_cbranch_execz .Lpad_G0_18
	s_lshl_b32 s16, s13, 10
	s_or_b32 s18, s17, 1
	v_readlane_b32 s9, v254, 25
	s_and_b64 s[8:9], s[8:9], exec
	s_cselect_b32 s6, s18, s17
	v_readlane_b32 s8, v254, 26
	s_sub_i32 s10, 0, s15
.Lpad_G0_12:
	s_cbranch_execz .Lpad_G0_19
	v_readfirstlane_b32 s19, v2
	s_mul_i32 s6, s6, s8
	v_readlane_b32 s8, v254, 27
	s_mul_i32 s10, s10, s19
	s_add_i32 s6, s6, s8
	s_mul_hi_u32 s10, s19, s10
	s_abs_i32 s9, s6
.Lpad_G0_13:
	s_cbranch_execz .Lpad_G0_20
	s_add_i32 s19, s19, s10
	s_mul_hi_u32 s10, s9, s19
	s_mul_i32 s11, s10, s15
	s_sub_i32 s9, s9, s11
	s_ashr_i32 s8, s6, 31
	s_add_i32 s11, s10, 1
	s_sub_i32 s20, s9, s15
.Lpad_G0_14:
	s_cbranch_execz .Lpad_G0_21
	s_cmp_ge_u32 s9, s15
	s_cselect_b32 s10, s11, s10
	s_cselect_b32 s9, s20, s9
	s_add_i32 s11, s10, 1
	s_cmp_ge_u32 s9, s15
	s_cselect_b32 s9, s11, s10
	s_xor_b32 s9, s9, s8
.Lpad_G0_15:
	s_cbranch_execz .Lpad_G0_22
	s_sub_i32 s8, s9, s8
	s_lshl_b32 s10, s8, 2
	s_sub_i32 s9, 64, s10
	s_min_i32 s11, s9, 4
	s_mul_i32 s8, s8, s15
	s_sub_i32 s20, s6, s8
	s_sext_i32_i8 s8, s11
.Lpad_G0_16:
	s_cbranch_execz .Lpad_G0_23
	v_cvt_f32_i32_e32 v3, s8
	s_sext_i32_i8 s6, s20
	v_cvt_f32_i32_e32 v2, s6
	s_xor_b32 s9, s6, s8
	v_rcp_iflag_f32_e32 v4, v3
	s_ashr_i32 s9, s9, 30
	s_or_b32 s21, s9, 1
.Lpad_G0_17:
	s_cbranch_execz .Lpad_G0_24
	v_mov_b32_e32 v135, v1
	v_mul_f32_e32 v4, v2, v4
	v_trunc_f32_e32 v4, v4
	v_fma_f32 v2, -v4, v3, v2
	v_cvt_i32_f32_e32 v4, v4
	v_cmp_ge_f32_e64 s[8:9], |v2|, |v3|
	s_and_b64 s[8:9], s[8:9], exec
.Lpad_G0_18:
	s_cbranch_execz .Lpad_G0_25
	s_cselect_b32 s6, s21, 0
	v_readfirstlane_b32 s8, v4
	s_add_i32 s6, s8, s6
	s_mul_i32 s8, s6, s11
	s_sub_i32 s8, s20, s8
	s_sext_i32_i8 s8, s8
	s_add_i32 s84, s10, s8
.Lpad_G0_19:
	s_cbranch_execz .Lpad_G0_26
	s_ashr_i32 s8, s84, 31
	s_mul_i32 s8, s54, s8
	s_mul_hi_u32 s9, s54, s84
	s_bfe_u32 s10, s12, 0x10017
	s_add_i32 s8, s9, s8
	s_mul_i32 s9, s10, s84
	s_add_i32 s21, s8, s9
.Lpad_G0_20:
	s_cbranch_execz .Lpad_G0_27
	s_bfe_i64 s[8:9], s[6:7], 0x80000
	s_mul_i32 s9, s54, s9
	s_mul_hi_u32 s11, s54, s8
	s_add_i32 s9, s11, s9
	s_mul_i32 s10, s10, s8
	s_add_i32 s9, s9, s10
	s_mul_i32 s8, s54, s8
.Lpad_G0_21:
	s_cbranch_execz .Lpad_G0_28
	s_add_u32 s10, s52, s8
	s_addc_u32 s11, s53, s9
	s_add_i32 s20, s16, 0
	s_add_i32 m0, s20, 0x10000
	s_mul_i32 s40, s54, s84
	global_load_lds_dwordx4 v134, s[10:11]
	s_add_i32 m0, s20, 0x12000
.Lpad_G0_22:
	s_cbranch_execz .Lpad_G0_29
	s_add_u32 s8, s10, s38
	global_load_lds_dwordx4 v130, s[10:11]
	s_addc_u32 s9, s11, 0
	s_add_i32 m0, s20, 0x14000
	v_mov_b32_e32 v131, v1
	global_load_lds_dwordx4 v134, s[8:9]
	s_add_i32 m0, s20, 0x16000
.Lpad_G0_23:
	s_cbranch_execz .Lpad_G0_30
	v_lshl_add_u64 v[6:7], s[8:9], 0, v[134:135]
	v_lshl_add_u64 v[8:9], s[8:9], 0, v[130:131]
	global_load_lds_dwordx4 v130, s[8:9]
	s_add_u32 s8, s44, s40
	s_addc_u32 s9, s45, s21
	s_add_i32 s21, s20, 0x2000
	s_mov_b32 m0, s20
.Lpad_G0_24:
	s_cbranch_execz .Lpad_G0_31
	s_add_u32 s40, s8, s38
	global_load_lds_dwordx4 v136, s[8:9]
	s_mov_b32 m0, s21
	s_addc_u32 s41, s9, 0
	s_add_i32 s49, s20, 0x4000
	s_mov_b64 s[96:97], s[62:63]
	global_load_lds_dwordx4 v132, s[8:9]
.Lpad_G0_25:
	s_cbranch_execz .Lpad_G0_32
	s_mov_b32 m0, s49
	s_add_i32 s62, s20, 0x6000
	global_load_lds_dwordx4 v136, s[40:41]
	s_mov_b32 m0, s62
	v_mov_b32_e32 v137, v1
	global_load_lds_dwordx4 v132, s[40:41]
	v_mov_b32_e32 v133, v1
.Lpad_G0_26:
	s_cbranch_execz .Lpad_G0_33
	s_cmp_eq_u32 s5, 1
	v_lshl_add_u64 v[2:3], s[10:11], 0, v[134:135]
	v_lshl_add_u64 v[4:5], s[10:11], 0, v[130:131]
	v_lshl_add_u64 v[10:11], s[8:9], 0, v[136:137]
	v_lshl_add_u64 v[12:13], s[8:9], 0, v[132:133]
	s_cselect_b64 s[56:57], -1, 0
	s_cmp_lg_u32 s5, 1
.Lpad_G0_27:
	s_cbranch_execz .Lpad_G0_34
	s_cbranch_scc1 .LBB0_340
	s_barrier

.Lpad_G0_28:
	s_cbranch_execz .Lpad_G0_35
	v_lshl_add_u64 v[2:3], v[4:5], 0, s[34:35]
	s_add_i32 m0, s20, 0x1a000
	s_add_i32 s68, s20, 0x8000
	global_load_lds_dwordx4 v[2:3], off
	v_lshl_add_u64 v[2:3], v[10:11], 0, s[34:35]
	s_mov_b32 m0, s68
	s_add_i32 s70, s20, 0xa000
.Lpad_G0_29:
	s_cbranch_execz .Lpad_G0_36
	global_load_lds_dwordx4 v[2:3], off
	v_lshl_add_u64 v[2:3], v[12:13], 0, s[34:35]
	s_mov_b32 m0, s70
	v_and_b32_e32 v20, 48, v0
	global_load_lds_dwordx4 v[2:3], off
	s_add_i32 m0, s20, 0x1c000
	v_lshl_add_u64 v[2:3], v[6:7], 0, s[34:35]
.Lpad_G0_30:
	s_cbranch_execz .Lpad_G0_37
	global_load_lds_dwordx4 v[2:3], off
	v_lshl_add_u64 v[2:3], v[8:9], 0, s[34:35]
	s_add_i32 m0, s20, 0x1e000
	v_and_b32_e32 v21, 15, v0
	global_load_lds_dwordx4 v[2:3], off
	v_lshl_or_b32 v20, v21, 6, v20
	v_lshlrev_b32_e32 v21, 2, v0
.Lpad_G0_31:
	s_cbranch_execz .Lpad_G0_38
	v_and_b32_e32 v143, 63, v0
	v_add_u32_e32 v0, v19, v17
	s_sext_i32_i8 s87, s6
	s_and_b32 s13, s13, 3
	s_lshr_b32 s63, s12, 6
	s_lshl_b32 s6, s5, 13
	v_and_b32_e32 v21, 32, v21
.Lpad_G0_32:
	s_cbranch_execz .Lpad_G0_39
	v_add_lshl_u32 v0, v0, v18, 1
	v_bitop3_b32 v22, v20, s6, v21 bitop3:0xde
	s_lshl_b32 s6, s13, 12
	s_waitcnt vmcnt(6)
	s_add_i32 s72, s63, -2
	v_lshl_add_u64 v[138:139], s[38:39], 0, v[0:1]
	v_add_u32_e32 v0, v16, v14
.Lpad_G0_33:
	s_cbranch_execz .Lpad_G0_40
	s_cmpk_lt_u32 s7, 0x100
	v_add_lshl_u32 v0, v0, v15, 1
	v_bitop3_b32 v142, v20, s6, v21 bitop3:0xde
	s_cselect_b64 s[6:7], -1, 0
	s_lshl_b32 s73, s13, 6
	s_lshl_b32 s78, s5, 7
	s_lshl_b32 s58, s14, 5
.Lpad_G0_34:
	s_cbranch_execz .Lpad_G0_41
	s_mov_b32 s59, s39
	s_mov_b32 s5, s39
	s_mul_i32 s64, s14, 0xa0
	s_mov_b32 s65, s39
	v_lshl_add_u64 v[140:141], s[38:39], 0, v[0:1]
	s_mov_b32 s79, 0
	v_add_u32_e32 v144, 0, v22

.Lpad_G0_36:
	s_cbranch_execz .Lpad_G0_43
	s_mov_b64 s[8:9], s[42:43]
	s_cbranch_vccz .LBB0_356

.Lpad_G0_37:
	s_cbranch_execz .Lpad_G0_44
	s_add_u32 s12, s12, s2
	s_addc_u32 s13, s13, s76
	v_mov_b64_e32 v[2:3], s[4:5]
	v_cmp_ge_i64_e32 vcc, s[12:13], v[2:3]
	v_cmp_lt_i64_e64 s[42:43], s[12:13], v[2:3]
	s_cbranch_vccnz .LBB0_345
	s_ashr_i32 s13, s12, 31
.Lpad_G0_38:
	s_cbranch_execz .Lpad_G0_45
	s_lshr_b32 s13, s13, 29
	s_add_i32 s13, s12, s13
	s_ashr_i32 s40, s13, 3
	s_and_b32 s13, s13, -8
	s_sub_i32 s12, s12, s13
	s_cmp_lt_i32 s12, 0
	s_cselect_b32 s13, s18, s17
.Lpad_G0_39:
	s_cbranch_execz .Lpad_G0_46
	s_mul_i32 s12, s13, s12
	s_add_i32 s12, s12, s40
	s_abs_i32 s40, s12
	s_mul_hi_u32 s41, s40, s19
	s_mul_i32 s66, s41, s15
	s_sub_i32 s40, s40, s66
	s_ashr_i32 s13, s12, 31
.Lpad_G0_40:
	s_cbranch_execz .Lpad_G0_47
	s_add_i32 s66, s41, 1
	s_sub_i32 s67, s40, s15
	s_cmp_ge_u32 s40, s15
	s_cselect_b32 s41, s66, s41
	s_cselect_b32 s40, s67, s40
	s_add_i32 s66, s41, 1
	s_cmp_ge_u32 s40, s15
.Lpad_G0_41:
	s_cbranch_execz .Lpad_G0_48
	s_cselect_b32 s40, s66, s41
	s_xor_b32 s40, s40, s13
	s_sub_i32 s13, s40, s13
	s_lshl_b32 s40, s13, 2
	s_sub_i32 s41, 64, s40
	s_min_i32 s41, s41, 4
	s_abs_i32 s66, s41
.Lpad_G0_42:
	s_cbranch_execz .Lpad_G0_49
	v_cvt_f32_u32_e32 v0, s66
	s_sub_i32 s85, 0, s66
	s_mul_i32 s13, s13, s15
	s_sub_i32 s12, s12, s13
	v_rcp_iflag_f32_e32 v0, v0
	s_abs_i32 s67, s12
	s_xor_b32 s13, s12, s41
.Lpad_G0_43:
	s_cbranch_execz .Lpad_G0_50
	s_ashr_i32 s13, s13, 31
	v_mul_f32_e32 v0, 0x4f7ffffe, v0
	v_cvt_u32_f32_e32 v0, v0
	s_nop 0
	v_readfirstlane_b32 s86, v0
	s_mul_i32 s85, s85, s86
	s_mul_hi_u32 s85, s86, s85
.Lpad_G0_44:
	s_cbranch_execz .Lpad_G0_51
	s_add_i32 s86, s86, s85
	s_mul_hi_u32 s85, s67, s86
	s_mul_i32 s86, s85, s66
	s_sub_i32 s67, s67, s86
	s_add_i32 s86, s85, 1
	s_sub_i32 s88, s67, s66
	s_cmp_ge_u32 s67, s66
.Lpad_G0_45:
	s_cbranch_execz .Lpad_G0_52
	s_cselect_b32 s85, s86, s85
	s_cselect_b32 s67, s88, s67
	s_add_i32 s86, s85, 1
	s_cmp_ge_u32 s67, s66
	s_cselect_b32 s66, s86, s85
	s_xor_b32 s66, s66, s13
	s_sub_i32 s85, s66, s13
.Lpad_G0_46:
	s_cbranch_execz .Lpad_G0_53
	s_mul_i32 s13, s85, s41
	s_sub_i32 s12, s12, s13
	s_add_i32 s86, s12, s40

.Lpad_G0_47:
	s_cbranch_execz .Lpad_G0_54
	s_mov_b64 s[42:43], s[8:9]
	s_cbranch_vccnz .LBB0_347
	s_ashr_i32 s12, s86, 31
	s_mul_hi_u32 s13, s54, s86
	s_mul_i32 s12, s54, s12
	s_add_i32 s12, s13, s12
	s_mul_i32 s13, s55, s86
.Lpad_G0_48:
	s_cbranch_execz .Lpad_G0_55
	s_add_i32 s12, s12, s13
	s_mul_i32 s13, s54, s86
	s_add_u32 s42, s44, s13
	s_addc_u32 s43, s45, s12

.Lpad_G0_49:
	s_cbranch_execz .Lpad_G0_56
	s_ashr_i32 s12, s85, 31
	s_mul_hi_u32 s13, s54, s85
	s_mul_i32 s12, s54, s12
	s_add_i32 s12, s13, s12
	s_mul_i32 s13, s55, s85
	s_add_i32 s12, s12, s13
	s_mul_i32 s13, s54, s85
.Lpad_G0_50:
	s_cbranch_execz .Lpad_G0_57
	s_add_u32 s66, s52, s13
	s_addc_u32 s67, s53, s12

.Lpad_G0_51:
	s_cbranch_execz .Lpad_G0_58
	s_mov_b32 s10, 0
	v_mov_b32_e32 v3, v2
	v_mov_b32_e32 v4, v2
	v_mov_b32_e32 v5, v2
	v_mov_b32_e32 v6, v2
	v_mov_b32_e32 v7, v2
	v_mov_b32_e32 v8, v2
.Lpad_G0_52:
	s_cbranch_execz .Lpad_G0_59
	v_mov_b32_e32 v9, v2
	v_mov_b32_e32 v10, v2
	v_mov_b32_e32 v11, v2
	v_mov_b32_e32 v12, v2
	v_mov_b32_e32 v13, v2
	v_mov_b32_e32 v18, v2
	v_mov_b32_e32 v19, v2
.Lpad_G0_53:
	s_cbranch_execz .Lpad_G0_60
	v_mov_b32_e32 v20, v2
	v_mov_b32_e32 v21, v2
	v_mov_b32_e32 v26, v2
	v_mov_b32_e32 v27, v2
	v_mov_b32_e32 v28, v2
	v_mov_b32_e32 v29, v2
	v_mov_b32_e32 v34, v2
.Lpad_G0_54:
	s_cbranch_execz .Lpad_G0_61
	v_mov_b32_e32 v35, v2
	v_mov_b32_e32 v36, v2
	v_mov_b32_e32 v37, v2
	v_mov_b32_e32 v42, v2
	v_mov_b32_e32 v43, v2
	v_mov_b32_e32 v44, v2
	v_mov_b32_e32 v45, v2
.Lpad_G0_55:
	s_cbranch_execz .Lpad_G0_62
	v_mov_b32_e32 v50, v2
	v_mov_b32_e32 v51, v2
	v_mov_b32_e32 v52, v2
	v_mov_b32_e32 v53, v2
	v_mov_b32_e32 v14, v2
	v_mov_b32_e32 v15, v2
	v_mov_b32_e32 v16, v2
.Lpad_G0_56:
	s_cbranch_execz .Lpad_G0_63
	v_mov_b32_e32 v17, v2
	v_mov_b32_e32 v22, v2
	v_mov_b32_e32 v23, v2
	v_mov_b32_e32 v24, v2
	v_mov_b32_e32 v25, v2
	v_mov_b32_e32 v30, v2
	v_mov_b32_e32 v31, v2
.Lpad_G0_57:
	s_cbranch_execz .Lpad_G0_64
	v_mov_b32_e32 v32, v2
	v_mov_b32_e32 v33, v2
	v_mov_b32_e32 v38, v2
	v_mov_b32_e32 v39, v2
	v_mov_b32_e32 v40, v2
	v_mov_b32_e32 v41, v2
	v_mov_b32_e32 v46, v2
.Lpad_G0_58:
	s_cbranch_execz .Lpad_G0_65
	v_mov_b32_e32 v47, v2
	v_mov_b32_e32 v48, v2
	v_mov_b32_e32 v49, v2
	v_mov_b32_e32 v54, v2
	v_mov_b32_e32 v55, v2
	v_mov_b32_e32 v56, v2
	v_mov_b32_e32 v57, v2
.Lpad_G0_59:
	s_cbranch_execz .Lpad_G0_66
	v_mov_b32_e32 v58, v2
	v_mov_b32_e32 v59, v2
	v_mov_b32_e32 v60, v2
	v_mov_b32_e32 v61, v2
	v_mov_b32_e32 v62, v2
	v_mov_b32_e32 v63, v2
	v_mov_b32_e32 v64, v2
.Lpad_G0_60:
	s_cbranch_execz .Lpad_G0_67
	v_mov_b32_e32 v65, v2
	v_mov_b32_e32 v66, v2
	v_mov_b32_e32 v67, v2
	v_mov_b32_e32 v68, v2
	v_mov_b32_e32 v69, v2
	v_mov_b32_e32 v70, v2
	v_mov_b32_e32 v71, v2
.Lpad_G0_61:
	s_cbranch_execz .Lpad_G0_68
	v_mov_b32_e32 v72, v2
	v_mov_b32_e32 v73, v2
	v_mov_b32_e32 v74, v2
	v_mov_b32_e32 v75, v2
	v_mov_b32_e32 v76, v2
	v_mov_b32_e32 v77, v2
	v_mov_b32_e32 v82, v2
.Lpad_G0_62:
	s_cbranch_execz .Lpad_G0_69
	v_mov_b32_e32 v83, v2
	v_mov_b32_e32 v84, v2
	v_mov_b32_e32 v85, v2
	v_mov_b32_e32 v90, v2
	v_mov_b32_e32 v91, v2
	v_mov_b32_e32 v92, v2
	v_mov_b32_e32 v93, v2
.Lpad_G0_63:
	s_cbranch_execz .Lpad_G0_70
	v_mov_b32_e32 v98, v2
	v_mov_b32_e32 v99, v2
	v_mov_b32_e32 v100, v2
	v_mov_b32_e32 v101, v2
	v_mov_b32_e32 v106, v2
	v_mov_b32_e32 v107, v2
	v_mov_b32_e32 v108, v2
.Lpad_G0_64:
	s_cbranch_execz .Lpad_G0_71
	v_mov_b32_e32 v109, v2
	v_mov_b32_e32 v114, v2
	v_mov_b32_e32 v115, v2
	v_mov_b32_e32 v116, v2
	v_mov_b32_e32 v117, v2
	v_mov_b32_e32 v78, v2
	v_mov_b32_e32 v79, v2
.Lpad_G0_65:
	s_cbranch_execz .Lpad_G0_72
	v_mov_b32_e32 v80, v2
	v_mov_b32_e32 v81, v2
	v_mov_b32_e32 v86, v2
	v_mov_b32_e32 v87, v2
	v_mov_b32_e32 v88, v2
	v_mov_b32_e32 v89, v2
	v_mov_b32_e32 v94, v2
.Lpad_G0_66:
	s_cbranch_execz .Lpad_G0_73
	v_mov_b32_e32 v95, v2
	v_mov_b32_e32 v96, v2
	v_mov_b32_e32 v97, v2
	v_mov_b32_e32 v102, v2
	v_mov_b32_e32 v103, v2
	v_mov_b32_e32 v104, v2
	v_mov_b32_e32 v105, v2
.Lpad_G0_67:
	s_cbranch_execz .Lpad_G0_74
	v_mov_b32_e32 v110, v2
	v_mov_b32_e32 v111, v2
	v_mov_b32_e32 v112, v2
	v_mov_b32_e32 v113, v2
	v_mov_b32_e32 v118, v2
	v_mov_b32_e32 v119, v2
	v_mov_b32_e32 v120, v2
.Lpad_G0_68:
	s_cbranch_execz .Lpad_G0_75
	v_mov_b32_e32 v121, v2
	v_mov_b32_e32 v122, v2
	v_mov_b32_e32 v123, v2
	v_mov_b32_e32 v124, v2
	v_mov_b32_e32 v125, v2
	v_mov_b32_e32 v126, v2
	v_mov_b32_e32 v127, v2
.Lpad_G0_69:
	s_cbranch_execz .Lpad_G0_76
	v_mov_b32_e32 v128, v2
	v_mov_b32_e32 v129, v2

.Lpad_G0_70:
	s_cbranch_execz .Lpad_G0_77
	s_add_u32 s10, s46, s8
	v_mov_b32_e32 v0, v143
	s_addc_u32 s11, s47, s9
	s_lshl_b32 s8, s87, 8
	s_ashr_i32 s9, s8, 31
	v_lshlrev_b32_e32 v145, 1, v0
	s_lshl_b64 s[8:9], s[8:9], 1
.Lpad_G0_71:
	s_cbranch_execz .Lpad_G0_78
	v_and_or_b32 v145, v145, 30, s78
	s_add_u32 s8, s10, s8
	v_mul_lo_u32 v145, v145, s14
	v_and_b32_e32 v0, -16, v0
	s_addc_u32 s9, s11, s9
	v_add3_u32 v0, v0, s73, v145
	v_lshl_add_u64 v[146:147], s[8:9], 0, v[0:1]
.Lpad_G0_72:
	s_cbranch_execz .Lpad_G0_79
	v_cvt_pk_bf16_f32 v126, v126, v127
	v_cvt_pk_bf16_f32 v127, v128, v129
	v_cvt_pk_bf16_f32 v128, v122, v123
	v_cvt_pk_bf16_f32 v129, v124, v125
	global_store_dwordx4 v0, v[126:129], s[8:9]
	v_cvt_pk_bf16_f32 v114, v114, v115
	v_cvt_pk_bf16_f32 v115, v116, v117
	v_cvt_pk_bf16_f32 v116, v106, v107
	v_cvt_pk_bf16_f32 v117, v108, v109
	global_store_dwordx4 v0, v[114:117], s[8:9] offset:256
.Lpad_G0_73:
	s_cbranch_execz .Lpad_G0_80
	v_cvt_pk_bf16_f32 v106, v118, v119
	v_cvt_pk_bf16_f32 v107, v120, v121
	v_cvt_pk_bf16_f32 v108, v110, v111
	v_lshl_add_u64 v[110:111], v[146:147], 0, s[58:59]
	v_cvt_pk_bf16_f32 v109, v112, v113
	global_store_dwordx4 v[110:111], v[106:109], off
	v_cvt_pk_bf16_f32 v98, v98, v99
	v_cvt_pk_bf16_f32 v99, v100, v101
	v_cvt_pk_bf16_f32 v100, v90, v91
	v_cvt_pk_bf16_f32 v101, v92, v93
	global_store_dwordx4 v[110:111], v[98:101], off offset:256
.Lpad_G0_74:
	s_cbranch_execz .Lpad_G0_81
	v_cvt_pk_bf16_f32 v90, v102, v103
	v_cvt_pk_bf16_f32 v91, v104, v105
	v_cvt_pk_bf16_f32 v92, v94, v95
	v_lshl_add_u64 v[94:95], v[110:111], 0, s[58:59]
	v_cvt_pk_bf16_f32 v93, v96, v97
	global_store_dwordx4 v[94:95], v[90:93], off
	v_cvt_pk_bf16_f32 v82, v82, v83
	v_cvt_pk_bf16_f32 v83, v84, v85
	v_cvt_pk_bf16_f32 v84, v74, v75
	v_cvt_pk_bf16_f32 v85, v76, v77
	global_store_dwordx4 v[94:95], v[82:85], off offset:256
.Lpad_G0_75:
	s_cbranch_execz .Lpad_G0_82
	v_cvt_pk_bf16_f32 v74, v86, v87
	v_cvt_pk_bf16_f32 v75, v88, v89
	v_cvt_pk_bf16_f32 v76, v78, v79
	v_lshl_add_u64 v[78:79], v[94:95], 0, s[58:59]
	v_cvt_pk_bf16_f32 v77, v80, v81
	global_store_dwordx4 v[78:79], v[74:77], off
	v_cvt_pk_bf16_f32 v70, v70, v71
	v_cvt_pk_bf16_f32 v71, v72, v73
	v_cvt_pk_bf16_f32 v72, v66, v67
	v_cvt_pk_bf16_f32 v73, v68, v69
	global_store_dwordx4 v[78:79], v[70:73], off offset:256
.Lpad_G0_76:
	s_cbranch_execz .Lpad_G0_83
	v_cvt_pk_bf16_f32 v62, v62, v63
	v_cvt_pk_bf16_f32 v63, v64, v65
	v_cvt_pk_bf16_f32 v64, v58, v59
	v_lshl_add_u64 v[58:59], v[78:79], 0, s[64:65]
	v_cvt_pk_bf16_f32 v65, v60, v61
	global_store_dwordx4 v[58:59], v[62:65], off
	v_cvt_pk_bf16_f32 v50, v50, v51
	v_cvt_pk_bf16_f32 v51, v52, v53
	v_cvt_pk_bf16_f32 v52, v42, v43
	v_cvt_pk_bf16_f32 v53, v44, v45
	global_store_dwordx4 v[58:59], v[50:53], off offset:256
.Lpad_G0_77:
	s_cbranch_execz .Lwalk_done
	v_cvt_pk_bf16_f32 v42, v54, v55
	v_cvt_pk_bf16_f32 v43, v56, v57
	v_cvt_pk_bf16_f32 v44, v46, v47
	v_lshl_add_u64 v[46:47], v[58:59], 0, s[58:59]
	v_cvt_pk_bf16_f32 v45, v48, v49
	global_store_dwordx4 v[46:47], v[42:45], off
	v_cvt_pk_bf16_f32 v34, v34, v35
	v_cvt_pk_bf16_f32 v35, v36, v37
	v_cvt_pk_bf16_f32 v36, v26, v27
	v_cvt_pk_bf16_f32 v37, v28, v29
	global_store_dwordx4 v[46:47], v[34:37], off offset:256
.Lpad_G0_78:
	s_cbranch_execz .Lwalk_done
	v_cvt_pk_bf16_f32 v26, v38, v39
	v_cvt_pk_bf16_f32 v27, v40, v41
	v_cvt_pk_bf16_f32 v28, v30, v31
	v_lshl_add_u64 v[30:31], v[46:47], 0, s[58:59]
	v_cvt_pk_bf16_f32 v29, v32, v33
	global_store_dwordx4 v[30:31], v[26:29], off
	v_cvt_pk_bf16_f32 v18, v18, v19
	v_cvt_pk_bf16_f32 v19, v20, v21
	v_cvt_pk_bf16_f32 v20, v10, v11
	v_cvt_pk_bf16_f32 v21, v12, v13
	global_store_dwordx4 v[30:31], v[18:21], off offset:256
.Lpad_G0_79:
	s_cbranch_execz .Lwalk_done
	v_cvt_pk_bf16_f32 v10, v22, v23
	v_cvt_pk_bf16_f32 v11, v24, v25
	v_cvt_pk_bf16_f32 v12, v14, v15
	v_lshl_add_u64 v[14:15], v[30:31], 0, s[58:59]
	s_and_b64 vcc, exec, s[40:41]
	s_mov_b64 s[8:9], -1
	v_cvt_pk_bf16_f32 v13, v16, v17
	global_store_dwordx4 v[14:15], v[10:13], off
.Lpad_G0_80:
	s_cbranch_execz .Lwalk_done
	v_cvt_pk_bf16_f32 v6, v6, v7
	v_cvt_pk_bf16_f32 v7, v8, v9
	v_cvt_pk_bf16_f32 v8, v2, v3
	v_cvt_pk_bf16_f32 v9, v4, v5
	global_store_dwordx4 v[14:15], v[6:9], off offset:256
	s_cbranch_vccnz .LBB0_342
	s_andn2_b64 vcc, exec, s[56:57]
.Lpad_G0_81:
	s_cbranch_execz .Lwalk_done
	s_cbranch_vccnz .LBB0_341
	s_barrier
	s_branch .LBB0_341

.Lpad_G0_82:
	s_cbranch_execz .Lwalk_done
	s_mov_b32 s70, 0x2aaaaaab
	s_mov_b32 s79, 0x24000
	s_mov_b32 s84, 0x49000
	s_mov_b32 s85, 0x6d000
	s_mov_b32 s86, 0xbfff
	s_mov_b64 s[64:65], 0x29100000
	s_mov_b64 s[66:67], 0x2000
.Lpad_G0_83:
	s_cbranch_execz .Lwalk_done
	s_mov_b64 s[72:73], 0x26000
	v_readlane_b32 s21, v252, 1
	s_mov_b64 s[62:63], s[96:97]
	s_barrier

.Lwalk_entry:
	s_mov_b64 exec, s[4:5]
	s_nop 1
	v_readfirstlane_b32 s6, v163
	s_nop 3
	s_mov_b64 exec, 0
	s_lshr_b32 s6, s6, 6
	s_add_i32 s7, s42, -2
	s_cmp_lt_i32 s7, 0
	s_cbranch_scc1 .Lwalk_done
	s_cmp_ge_i32 s7, 9
	s_cbranch_scc0 .Lwalk_modok
	s_add_i32 s7, s7, -9
.Lwalk_modok:
	s_cmp_eq_u32 s7, 6
	s_cbranch_scc1 .Lwalk_sel_G2
	s_cmp_eq_u32 s7, 2
	s_cbranch_scc1 .Lwalk_sel_GM
	s_cmp_eq_u32 s7, 0
	s_cbranch_scc1 .Lwalk_sel_G0
	s_cmp_eq_u32 s7, 4
	s_cbranch_scc1 .Lwalk_sel_G0
	s_cmp_eq_u32 s7, 7
	s_cbranch_scc1 .Lwalk_sel_G0
	s_branch .Lwalk_done
.Lwalk_sel_G2:
	s_cmp_eq_u32 s6, 1
	s_cbranch_scc1 .Lpad_G2_0
	s_cmp_eq_u32 s6, 2
	s_cbranch_scc1 .Lpad_G2_1
	s_cmp_eq_u32 s6, 3
	s_cbranch_scc1 .Lpad_G2_2
	s_cmp_eq_u32 s6, 4
	s_cbranch_scc1 .Lpad_G2_3
	s_cmp_eq_u32 s6, 5
	s_cbranch_scc1 .Lpad_G2_4
	s_cmp_eq_u32 s6, 6
	s_cbranch_scc1 .Lpad_G2_5
	s_branch .Lpad_G2_6

.Lwalk_done:
	s_branch .LBB0_638
.LBB0_638:
	s_or_b64 exec, exec, s[4:5]
	s_mov_b64 s[4:5], 0
	s_waitcnt lgkmcnt(0)
	s_barrier
